# non-temporal hint also on last-use residual loads of the three residual epilogues, prologue weight loads and HGRN final-state stores
# baseline (speedup 1.0000x reference)
.LBB0_22:
	s_lshl_b32 s16, s10, 1
	s_lshl_b32 s20, s9, 1
	v_add_u32_e32 v20, s16, v4
	v_add_u32_e32 v48, s20, v5
	v_add_u32_e32 v50, s16, v6
	v_add_u32_e32 v52, s20, v7
	v_add_u32_e32 v54, s16, v8
	v_add_u32_e32 v56, s20, v9
	v_add_u32_e32 v60, s16, v10
	v_add_u32_e32 v62, s20, v11
	v_add_u32_e32 v64, s16, v12
	v_add_u32_e32 v68, s20, v13
	v_add_u32_e32 v70, s16, v14
	v_add_u32_e32 v72, s20, v15
	v_add_u32_e32 v74, s16, v16
	v_add_u32_e32 v76, s20, v17
	v_add_u32_e32 v78, s16, v18
	v_add_u32_e32 v80, s20, v19
	v_ashrrev_i32_e32 v21, 31, v20
	v_ashrrev_i32_e32 v49, 31, v48
	v_ashrrev_i32_e32 v51, 31, v50
	v_ashrrev_i32_e32 v53, 31, v52
	v_ashrrev_i32_e32 v55, 31, v54
	v_ashrrev_i32_e32 v57, 31, v56
	v_ashrrev_i32_e32 v61, 31, v60
	v_ashrrev_i32_e32 v63, 31, v62
	v_ashrrev_i32_e32 v65, 31, v64
	v_ashrrev_i32_e32 v69, 31, v68
	v_ashrrev_i32_e32 v71, 31, v70
	v_ashrrev_i32_e32 v73, 31, v72
	v_ashrrev_i32_e32 v75, 31, v74
	v_ashrrev_i32_e32 v77, 31, v76
	v_ashrrev_i32_e32 v79, 31, v78
	v_ashrrev_i32_e32 v81, 31, v80
	v_lshlrev_b64 v[20:21], 12, v[20:21]
	v_lshlrev_b64 v[48:49], 12, v[48:49]
	v_lshlrev_b64 v[50:51], 12, v[50:51]
	v_lshlrev_b64 v[52:53], 12, v[52:53]
	v_lshlrev_b64 v[54:55], 12, v[54:55]
	v_lshlrev_b64 v[56:57], 12, v[56:57]
	v_lshlrev_b64 v[60:61], 12, v[60:61]
	v_lshlrev_b64 v[62:63], 12, v[62:63]
	v_lshlrev_b64 v[64:65], 12, v[64:65]
	v_lshlrev_b64 v[68:69], 12, v[68:69]
	v_lshlrev_b64 v[70:71], 12, v[70:71]
	v_lshlrev_b64 v[72:73], 12, v[72:73]
	v_lshlrev_b64 v[74:75], 12, v[74:75]
	v_lshlrev_b64 v[76:77], 12, v[76:77]
	v_lshlrev_b64 v[78:79], 12, v[78:79]
	v_lshlrev_b64 v[80:81], 12, v[80:81]
	v_lshl_add_u64 v[20:21], v[2:3], 0, v[20:21]
	v_lshl_add_u64 v[48:49], v[2:3], 0, v[48:49]
	v_lshl_add_u64 v[50:51], v[2:3], 0, v[50:51]
	v_lshl_add_u64 v[52:53], v[2:3], 0, v[52:53]
	v_lshl_add_u64 v[54:55], v[2:3], 0, v[54:55]
	v_lshl_add_u64 v[56:57], v[2:3], 0, v[56:57]
	v_lshl_add_u64 v[60:61], v[2:3], 0, v[60:61]
	v_lshl_add_u64 v[62:63], v[2:3], 0, v[62:63]
	v_lshl_add_u64 v[64:65], v[2:3], 0, v[64:65]
	v_lshl_add_u64 v[68:69], v[2:3], 0, v[68:69]
	v_lshl_add_u64 v[70:71], v[2:3], 0, v[70:71]
	v_lshl_add_u64 v[72:73], v[2:3], 0, v[72:73]
	v_lshl_add_u64 v[74:75], v[2:3], 0, v[74:75]
	v_lshl_add_u64 v[76:77], v[2:3], 0, v[76:77]
	v_lshl_add_u64 v[78:79], v[2:3], 0, v[78:79]
	v_lshl_add_u64 v[80:81], v[2:3], 0, v[80:81]
	global_load_dword v24, v[20:21], off nt
	global_load_dword v47, v[48:49], off nt
	global_load_dword v59, v[50:51], off nt
	global_load_dword v67, v[52:53], off nt
	global_load_dword v82, v[54:55], off nt
	global_load_dword v83, v[56:57], off nt
	global_load_dword v84, v[60:61], off nt
	global_load_dword v85, v[62:63], off nt
	global_load_dword v86, v[64:65], off nt
	global_load_dword v87, v[68:69], off nt
	global_load_dword v88, v[70:71], off nt
	global_load_dword v89, v[72:73], off nt
	global_load_dword v90, v[74:75], off nt
	global_load_dword v91, v[76:77], off nt
	global_load_dword v92, v[78:79], off nt
	global_load_dword v93, v[80:81], off nt
	s_add_i32 s10, s10, 16
	s_add_i32 s9, s9, 16
	s_add_i32 s11, s11, -16
	v_add_u32_e32 v20, s16, v22
	v_add_u32_e32 v48, s20, v1
	v_add_u32_e32 v50, s16, v32
	v_add_u32_e32 v52, s20, v23
	v_add_u32_e32 v54, s16, v34
	v_add_u32_e32 v56, s20, v27
	v_add_u32_e32 v60, s16, v36
	v_add_u32_e32 v62, s20, v29
	v_add_u32_e32 v64, s16, v38
	v_add_u32_e32 v68, s20, v33
	v_add_u32_e32 v70, s16, v40
	v_add_u32_e32 v72, s20, v35
	v_add_u32_e32 v74, s16, v42
	v_add_u32_e32 v76, s20, v37
	v_add_u32_e32 v78, s16, v44
	v_add_u32_e32 v80, s20, v39
	s_cmp_lg_u32 s11, 0
	v_mad_u64_u32 v[20:21], s[20:21], v20, s47, v[26:27]
	v_mad_u64_u32 v[48:49], s[20:21], v48, s47, v[26:27]
	v_mad_u64_u32 v[50:51], s[20:21], v50, s47, v[26:27]
	v_mad_u64_u32 v[52:53], s[20:21], v52, s47, v[26:27]
	v_mad_u64_u32 v[54:55], s[20:21], v54, s47, v[26:27]
	v_mad_u64_u32 v[56:57], s[20:21], v56, s47, v[26:27]
	v_mad_u64_u32 v[60:61], s[20:21], v60, s47, v[26:27]
	v_mad_u64_u32 v[62:63], s[20:21], v62, s47, v[26:27]
	v_mad_u64_u32 v[64:65], s[20:21], v64, s47, v[26:27]
	v_mad_u64_u32 v[68:69], s[20:21], v68, s47, v[26:27]
	v_mad_u64_u32 v[70:71], s[20:21], v70, s47, v[26:27]
	v_mad_u64_u32 v[72:73], s[20:21], v72, s47, v[26:27]
	v_mad_u64_u32 v[74:75], s[20:21], v74, s47, v[26:27]
	v_mad_u64_u32 v[76:77], s[20:21], v76, s47, v[26:27]
	v_mad_u64_u32 v[78:79], s[20:21], v78, s47, v[26:27]
	v_mad_u64_u32 v[80:81], s[20:21], v80, s47, v[26:27]
	s_waitcnt vmcnt(15)
	ds_write_b32 v20, v24
	s_waitcnt vmcnt(14)
	ds_write_b32 v48, v47
	s_waitcnt vmcnt(13)
	ds_write_b32 v50, v59
	s_waitcnt vmcnt(12)
	ds_write_b32 v52, v67
	s_waitcnt vmcnt(11)
	ds_write_b32 v54, v82
	s_waitcnt vmcnt(10)
	ds_write_b32 v56, v83
	s_waitcnt vmcnt(9)
	ds_write_b32 v60, v84
	s_waitcnt vmcnt(8)
	ds_write_b32 v62, v85
	s_waitcnt vmcnt(7)
	ds_write_b32 v64, v86
	s_waitcnt vmcnt(6)
	ds_write_b32 v68, v87
	s_waitcnt vmcnt(5)
	ds_write_b32 v70, v88
	s_waitcnt vmcnt(4)
	ds_write_b32 v72, v89
	s_waitcnt vmcnt(3)
	ds_write_b32 v74, v90
	s_waitcnt vmcnt(2)
	ds_write_b32 v76, v91
	s_waitcnt vmcnt(1)
	ds_write_b32 v78, v92
	s_waitcnt vmcnt(0)
	ds_write_b32 v80, v93
	s_cbranch_scc1 .LBB0_22
	s_mul_i32 s5, s5, 0x580000
	s_waitcnt lgkmcnt(0)
	s_add_u32 s5, s28, s5
	ds_read2_b32 v[6:7], v41 offset0:33 offset1:41
	ds_read2_b32 v[8:9], v41 offset1:8
	ds_read2_b32 v[10:11], v41 offset0:66 offset1:74
	ds_read2_b32 v[12:13], v41 offset0:99 offset1:107
	ds_read2_b32 v[14:15], v41 offset0:132 offset1:140
	ds_read2_b32 v[16:17], v41 offset0:165 offset1:173
	ds_read2_b32 v[18:19], v41 offset0:198 offset1:206
	ds_read2_b32 v[20:21], v41 offset0:231 offset1:239
	s_addc_u32 s9, s29, 0
	s_lshl_b32 s8, s8, 1
	s_add_u32 s8, s5, s8
	s_addc_u32 s9, s9, 0
	v_lshlrev_b32_e32 v24, 1, v28
	v_lshl_add_u64 v[48:49], s[8:9], 0, v[24:25]
	s_waitcnt lgkmcnt(6)
	v_cvt_pk_bf16_f32 v2, v8, v6
	v_add_u32_e32 v6, s4, v30
	s_waitcnt lgkmcnt(4)
	v_cvt_pk_bf16_f32 v3, v10, v12
	s_waitcnt lgkmcnt(2)
	v_cvt_pk_bf16_f32 v4, v14, v16
	s_waitcnt lgkmcnt(0)
	v_cvt_pk_bf16_f32 v5, v18, v20
	v_mad_i64_i32 v[50:51], s[8:9], v6, s48, v[48:49]
	global_store_dwordx4 v[50:51], v[2:5], off
	v_add_u32_e32 v6, s4, v43
	s_nop 0
	v_cvt_pk_bf16_f32 v2, v9, v7
	v_cvt_pk_bf16_f32 v3, v11, v13
	v_cvt_pk_bf16_f32 v4, v15, v17
	v_cvt_pk_bf16_f32 v5, v19, v21
	ds_read2_b32 v[8:9], v41 offset0:49 offset1:57
	ds_read2_b32 v[10:11], v41 offset0:16 offset1:24
	ds_read2_b32 v[12:13], v41 offset0:82 offset1:90
	ds_read2_b32 v[14:15], v41 offset0:115 offset1:123
	ds_read2_b32 v[16:17], v41 offset0:148 offset1:156
	ds_read2_b32 v[18:19], v41 offset0:181 offset1:189
	ds_read2_b32 v[20:21], v41 offset0:214 offset1:222
	ds_read2_b32 v[50:51], v41 offset0:247 offset1:255
	v_mad_i64_i32 v[6:7], s[8:9], v6, s48, v[48:49]
	global_store_dwordx4 v[6:7], v[2:5], off
	v_add_u32_e32 v6, s4, v45
	v_mad_i64_i32 v[6:7], s[8:9], v6, s48, v[48:49]
	s_waitcnt lgkmcnt(6)
	v_cvt_pk_bf16_f32 v2, v10, v8
	s_waitcnt lgkmcnt(4)
	v_cvt_pk_bf16_f32 v3, v12, v14
	s_waitcnt lgkmcnt(2)
	v_cvt_pk_bf16_f32 v4, v16, v18
	s_waitcnt lgkmcnt(0)
	v_cvt_pk_bf16_f32 v5, v20, v50
	global_store_dwordx4 v[6:7], v[2:5], off
	v_add_u32_e32 v6, s4, v58
	v_mad_i64_i32 v[6:7], s[4:5], v6, s48, v[48:49]
	v_cvt_pk_bf16_f32 v2, v11, v9
	v_cvt_pk_bf16_f32 v3, v13, v15
	v_cvt_pk_bf16_f32 v4, v17, v19
	v_cvt_pk_bf16_f32 v5, v21, v51
	global_store_dwordx4 v[6:7], v[2:5], off
	s_waitcnt lgkmcnt(0)
	s_mov_b64 s[4:5], 0

.LBB0_30:
	s_lshl_b32 s23, s21, 1
	s_lshl_b32 s53, s20, 1
	v_add_u32_e32 v20, s23, v4
	v_add_u32_e32 v24, s53, v5
	v_add_u32_e32 v47, s23, v6
	v_add_u32_e32 v52, s53, v7
	v_add_u32_e32 v54, s23, v8
	v_add_u32_e32 v56, s53, v9
	v_add_u32_e32 v59, s23, v10
	v_add_u32_e32 v62, s53, v11
	v_add_u32_e32 v64, s23, v12
	v_add_u32_e32 v67, s53, v13
	v_add_u32_e32 v70, s23, v14
	v_add_u32_e32 v72, s53, v15
	v_add_u32_e32 v74, s23, v16
	v_add_u32_e32 v76, s53, v17
	v_add_u32_e32 v78, s23, v18
	v_add_u32_e32 v80, s53, v19
	v_mad_i64_i32 v[20:21], s[24:25], v20, s49, v[2:3]
	v_mad_i64_i32 v[48:49], s[24:25], v24, s49, v[2:3]
	v_mad_i64_i32 v[50:51], s[24:25], v47, s49, v[2:3]
	v_mad_i64_i32 v[52:53], s[24:25], v52, s49, v[2:3]
	v_mad_i64_i32 v[54:55], s[24:25], v54, s49, v[2:3]
	v_mad_i64_i32 v[56:57], s[24:25], v56, s49, v[2:3]
	v_mad_i64_i32 v[60:61], s[24:25], v59, s49, v[2:3]
	v_mad_i64_i32 v[62:63], s[24:25], v62, s49, v[2:3]
	v_mad_i64_i32 v[64:65], s[24:25], v64, s49, v[2:3]
	v_mad_i64_i32 v[68:69], s[24:25], v67, s49, v[2:3]
	v_mad_i64_i32 v[70:71], s[24:25], v70, s49, v[2:3]
	v_mad_i64_i32 v[72:73], s[24:25], v72, s49, v[2:3]
	v_mad_i64_i32 v[74:75], s[24:25], v74, s49, v[2:3]
	v_mad_i64_i32 v[76:77], s[24:25], v76, s49, v[2:3]
	v_mad_i64_i32 v[78:79], s[24:25], v78, s49, v[2:3]
	v_mad_i64_i32 v[80:81], s[24:25], v80, s49, v[2:3]
	global_load_dword v24, v[20:21], off nt
	global_load_dword v47, v[48:49], off nt
	global_load_dword v59, v[50:51], off nt
	global_load_dword v67, v[52:53], off nt
	global_load_dword v82, v[54:55], off nt
	global_load_dword v83, v[56:57], off nt
	global_load_dword v84, v[60:61], off nt
	global_load_dword v85, v[62:63], off nt
	global_load_dword v86, v[64:65], off nt
	global_load_dword v87, v[68:69], off nt
	global_load_dword v88, v[70:71], off nt
	global_load_dword v89, v[72:73], off nt
	global_load_dword v90, v[74:75], off nt
	global_load_dword v91, v[76:77], off nt
	global_load_dword v92, v[78:79], off nt
	global_load_dword v93, v[80:81], off nt
	s_add_i32 s21, s21, 16
	s_add_i32 s20, s20, 16
	s_add_i32 s22, s22, -16
	v_add_u32_e32 v20, s23, v22
	v_add_u32_e32 v48, s53, v1
	v_add_u32_e32 v50, s23, v32
	v_add_u32_e32 v52, s53, v23
	v_add_u32_e32 v54, s23, v34
	v_add_u32_e32 v56, s53, v27
	v_add_u32_e32 v60, s23, v36
	v_add_u32_e32 v62, s53, v29
	v_add_u32_e32 v64, s23, v38
	v_add_u32_e32 v68, s53, v33
	v_add_u32_e32 v70, s23, v40
	v_add_u32_e32 v72, s53, v35
	v_add_u32_e32 v74, s23, v42
	v_add_u32_e32 v76, s53, v37
	v_add_u32_e32 v78, s23, v44
	v_add_u32_e32 v80, s53, v39
	s_cmp_lg_u32 s22, 0
	v_mad_u64_u32 v[20:21], s[24:25], v20, s47, v[26:27]
	v_mad_u64_u32 v[48:49], s[24:25], v48, s47, v[26:27]
	v_mad_u64_u32 v[50:51], s[24:25], v50, s47, v[26:27]
	v_mad_u64_u32 v[52:53], s[24:25], v52, s47, v[26:27]
	v_mad_u64_u32 v[54:55], s[24:25], v54, s47, v[26:27]
	v_mad_u64_u32 v[56:57], s[24:25], v56, s47, v[26:27]
	v_mad_u64_u32 v[60:61], s[24:25], v60, s47, v[26:27]
	v_mad_u64_u32 v[62:63], s[24:25], v62, s47, v[26:27]
	v_mad_u64_u32 v[64:65], s[24:25], v64, s47, v[26:27]
	v_mad_u64_u32 v[68:69], s[24:25], v68, s47, v[26:27]
	v_mad_u64_u32 v[70:71], s[24:25], v70, s47, v[26:27]
	v_mad_u64_u32 v[72:73], s[24:25], v72, s47, v[26:27]
	v_mad_u64_u32 v[74:75], s[24:25], v74, s47, v[26:27]
	v_mad_u64_u32 v[76:77], s[24:25], v76, s47, v[26:27]
	v_mad_u64_u32 v[78:79], s[24:25], v78, s47, v[26:27]
	v_mad_u64_u32 v[80:81], s[24:25], v80, s47, v[26:27]
	s_waitcnt vmcnt(15)
	ds_write_b32 v20, v24
	s_waitcnt vmcnt(14)
	ds_write_b32 v48, v47
	s_waitcnt vmcnt(13)
	ds_write_b32 v50, v59
	s_waitcnt vmcnt(12)
	ds_write_b32 v52, v67
	s_waitcnt vmcnt(11)
	ds_write_b32 v54, v82
	s_waitcnt vmcnt(10)
	ds_write_b32 v56, v83
	s_waitcnt vmcnt(9)
	ds_write_b32 v60, v84
	s_waitcnt vmcnt(8)
	ds_write_b32 v62, v85
	s_waitcnt vmcnt(7)
	ds_write_b32 v64, v86
	s_waitcnt vmcnt(6)
	ds_write_b32 v68, v87
	s_waitcnt vmcnt(5)
	ds_write_b32 v70, v88
	s_waitcnt vmcnt(4)
	ds_write_b32 v72, v89
	s_waitcnt vmcnt(3)
	ds_write_b32 v74, v90
	s_waitcnt vmcnt(2)
	ds_write_b32 v76, v91
	s_waitcnt vmcnt(1)
	ds_write_b32 v78, v92
	s_waitcnt vmcnt(0)
	ds_write_b32 v80, v93
	s_cbranch_scc1 .LBB0_30
	s_waitcnt lgkmcnt(0)
	s_cmp_lg_u64 s[8:9], 0
	s_cselect_b64 s[20:21], -1, 0
	s_cmp_eq_u64 s[8:9], 0
	s_cbranch_scc1 .LBB0_67
	s_lshl_b32 s22, s5, 12
	s_add_u32 s10, s10, s22
	s_addc_u32 s11, s11, 0
	s_add_u32 s8, s8, s22
	v_or_b32_e32 v2, s4, v28
	s_addc_u32 s9, s9, 0
	v_lshlrev_b32_e32 v6, 2, v2
	global_load_dwordx4 v[10:13], v6, s[8:9] offset:16
	global_load_dwordx4 v[14:17], v6, s[8:9]
	global_load_dwordx4 v[2:5], v6, s[10:11]
	s_nop 0
	global_load_dwordx4 v[6:9], v6, s[10:11] offset:16
	s_branch .LBB0_68

.LBB0_37:
	s_lshl_b32 s20, s11, 1
	s_lshl_b32 s21, s10, 1
	v_add_u32_e32 v20, s20, v4
	v_add_u32_e32 v48, s21, v5
	v_add_u32_e32 v50, s20, v6
	v_add_u32_e32 v52, s21, v7
	v_add_u32_e32 v54, s20, v8
	v_add_u32_e32 v56, s21, v9
	v_add_u32_e32 v60, s20, v10
	v_add_u32_e32 v62, s21, v11
	v_add_u32_e32 v64, s20, v12
	v_add_u32_e32 v68, s21, v13
	v_add_u32_e32 v70, s20, v14
	v_add_u32_e32 v72, s21, v15
	v_add_u32_e32 v74, s20, v16
	v_add_u32_e32 v76, s21, v17
	v_add_u32_e32 v78, s20, v18
	v_add_u32_e32 v80, s21, v19
	v_ashrrev_i32_e32 v21, 31, v20
	v_ashrrev_i32_e32 v49, 31, v48
	v_ashrrev_i32_e32 v51, 31, v50
	v_ashrrev_i32_e32 v53, 31, v52
	v_ashrrev_i32_e32 v55, 31, v54
	v_ashrrev_i32_e32 v57, 31, v56
	v_ashrrev_i32_e32 v61, 31, v60
	v_ashrrev_i32_e32 v63, 31, v62
	v_ashrrev_i32_e32 v65, 31, v64
	v_ashrrev_i32_e32 v69, 31, v68
	v_ashrrev_i32_e32 v71, 31, v70
	v_ashrrev_i32_e32 v73, 31, v72
	v_ashrrev_i32_e32 v75, 31, v74
	v_ashrrev_i32_e32 v77, 31, v76
	v_ashrrev_i32_e32 v79, 31, v78
	v_ashrrev_i32_e32 v81, 31, v80
	v_lshlrev_b64 v[20:21], 10, v[20:21]
	v_lshlrev_b64 v[48:49], 10, v[48:49]
	v_lshlrev_b64 v[50:51], 10, v[50:51]
	v_lshlrev_b64 v[52:53], 10, v[52:53]
	v_lshlrev_b64 v[54:55], 10, v[54:55]
	v_lshlrev_b64 v[56:57], 10, v[56:57]
	v_lshlrev_b64 v[60:61], 10, v[60:61]
	v_lshlrev_b64 v[62:63], 10, v[62:63]
	v_lshlrev_b64 v[64:65], 10, v[64:65]
	v_lshlrev_b64 v[68:69], 10, v[68:69]
	v_lshlrev_b64 v[70:71], 10, v[70:71]
	v_lshlrev_b64 v[72:73], 10, v[72:73]
	v_lshlrev_b64 v[74:75], 10, v[74:75]
	v_lshlrev_b64 v[76:77], 10, v[76:77]
	v_lshlrev_b64 v[78:79], 10, v[78:79]
	v_lshlrev_b64 v[80:81], 10, v[80:81]
	v_lshl_add_u64 v[20:21], v[2:3], 0, v[20:21]
	v_lshl_add_u64 v[48:49], v[2:3], 0, v[48:49]
	v_lshl_add_u64 v[50:51], v[2:3], 0, v[50:51]
	v_lshl_add_u64 v[52:53], v[2:3], 0, v[52:53]
	v_lshl_add_u64 v[54:55], v[2:3], 0, v[54:55]
	v_lshl_add_u64 v[56:57], v[2:3], 0, v[56:57]
	v_lshl_add_u64 v[60:61], v[2:3], 0, v[60:61]
	v_lshl_add_u64 v[62:63], v[2:3], 0, v[62:63]
	v_lshl_add_u64 v[64:65], v[2:3], 0, v[64:65]
	v_lshl_add_u64 v[68:69], v[2:3], 0, v[68:69]
	v_lshl_add_u64 v[70:71], v[2:3], 0, v[70:71]
	v_lshl_add_u64 v[72:73], v[2:3], 0, v[72:73]
	v_lshl_add_u64 v[74:75], v[2:3], 0, v[74:75]
	v_lshl_add_u64 v[76:77], v[2:3], 0, v[76:77]
	v_lshl_add_u64 v[78:79], v[2:3], 0, v[78:79]
	v_lshl_add_u64 v[80:81], v[2:3], 0, v[80:81]
	global_load_dword v24, v[20:21], off nt
	global_load_dword v47, v[48:49], off nt
	global_load_dword v59, v[50:51], off nt
	global_load_dword v67, v[52:53], off nt
	global_load_dword v82, v[54:55], off nt
	global_load_dword v83, v[56:57], off nt
	global_load_dword v84, v[60:61], off nt
	global_load_dword v85, v[62:63], off nt
	global_load_dword v86, v[64:65], off nt
	global_load_dword v87, v[68:69], off nt
	global_load_dword v88, v[70:71], off nt
	global_load_dword v89, v[72:73], off nt
	global_load_dword v90, v[74:75], off nt
	global_load_dword v91, v[76:77], off nt
	global_load_dword v92, v[78:79], off nt
	global_load_dword v93, v[80:81], off nt
	s_add_i32 s11, s11, 16
	s_add_i32 s10, s10, 16
	s_add_i32 s16, s16, -16
	v_add_u32_e32 v20, s20, v22
	v_add_u32_e32 v48, s21, v1
	v_add_u32_e32 v50, s20, v32
	v_add_u32_e32 v52, s21, v23
	v_add_u32_e32 v54, s20, v34
	v_add_u32_e32 v56, s21, v27
	v_add_u32_e32 v60, s20, v36
	v_add_u32_e32 v62, s21, v29
	v_add_u32_e32 v64, s20, v38
	v_add_u32_e32 v68, s21, v33
	v_add_u32_e32 v70, s20, v40
	v_add_u32_e32 v72, s21, v35
	v_add_u32_e32 v74, s20, v42
	v_add_u32_e32 v76, s21, v37
	v_add_u32_e32 v78, s20, v44
	v_add_u32_e32 v80, s21, v39
	s_cmp_lg_u32 s16, 0
	v_mad_u64_u32 v[20:21], s[20:21], v20, s47, v[26:27]
	v_mad_u64_u32 v[48:49], s[20:21], v48, s47, v[26:27]
	v_mad_u64_u32 v[50:51], s[20:21], v50, s47, v[26:27]
	v_mad_u64_u32 v[52:53], s[20:21], v52, s47, v[26:27]
	v_mad_u64_u32 v[54:55], s[20:21], v54, s47, v[26:27]
	v_mad_u64_u32 v[56:57], s[20:21], v56, s47, v[26:27]
	v_mad_u64_u32 v[60:61], s[20:21], v60, s47, v[26:27]
	v_mad_u64_u32 v[62:63], s[20:21], v62, s47, v[26:27]
	v_mad_u64_u32 v[64:65], s[20:21], v64, s47, v[26:27]
	v_mad_u64_u32 v[68:69], s[20:21], v68, s47, v[26:27]
	v_mad_u64_u32 v[70:71], s[20:21], v70, s47, v[26:27]
	v_mad_u64_u32 v[72:73], s[20:21], v72, s47, v[26:27]
	v_mad_u64_u32 v[74:75], s[20:21], v74, s47, v[26:27]
	v_mad_u64_u32 v[76:77], s[20:21], v76, s47, v[26:27]
	v_mad_u64_u32 v[78:79], s[20:21], v78, s47, v[26:27]
	v_mad_u64_u32 v[80:81], s[20:21], v80, s47, v[26:27]
	s_waitcnt vmcnt(15)
	ds_write_b32 v20, v24
	s_waitcnt vmcnt(14)
	ds_write_b32 v48, v47
	s_waitcnt vmcnt(13)
	ds_write_b32 v50, v59
	s_waitcnt vmcnt(12)
	ds_write_b32 v52, v67
	s_waitcnt vmcnt(11)
	ds_write_b32 v54, v82
	s_waitcnt vmcnt(10)
	ds_write_b32 v56, v83
	s_waitcnt vmcnt(9)
	ds_write_b32 v60, v84
	s_waitcnt vmcnt(8)
	ds_write_b32 v62, v85
	s_waitcnt vmcnt(7)
	ds_write_b32 v64, v86
	s_waitcnt vmcnt(6)
	ds_write_b32 v68, v87
	s_waitcnt vmcnt(5)
	ds_write_b32 v70, v88
	s_waitcnt vmcnt(4)
	ds_write_b32 v72, v89
	s_waitcnt vmcnt(3)
	ds_write_b32 v74, v90
	s_waitcnt vmcnt(2)
	ds_write_b32 v76, v91
	s_waitcnt vmcnt(1)
	ds_write_b32 v78, v92
	s_waitcnt vmcnt(0)
	ds_write_b32 v80, v93
	s_cbranch_scc1 .LBB0_37
	s_lshl_b64 s[4:5], s[4:5], 1
	s_waitcnt lgkmcnt(0)
	s_add_u32 s4, s37, s4
	ds_read2_b32 v[6:7], v41 offset0:33 offset1:41
	ds_read2_b32 v[8:9], v41 offset1:8
	ds_read2_b32 v[10:11], v41 offset0:66 offset1:74
	ds_read2_b32 v[12:13], v41 offset0:99 offset1:107
	ds_read2_b32 v[14:15], v41 offset0:132 offset1:140
	ds_read2_b32 v[16:17], v41 offset0:165 offset1:173
	ds_read2_b32 v[18:19], v41 offset0:198 offset1:206
	ds_read2_b32 v[20:21], v41 offset0:231 offset1:239
	s_addc_u32 s5, s38, s5
	s_lshl_b32 s9, s9, 1
	s_add_u32 s4, s4, s9
	v_add_u32_e32 v50, s8, v30
	s_addc_u32 s5, s5, 0
	v_lshlrev_b32_e32 v24, 1, v28
	v_ashrrev_i32_e32 v51, 31, v50
	v_lshl_add_u64 v[48:49], s[4:5], 0, v[24:25]
	v_lshlrev_b64 v[50:51], 9, v[50:51]
	s_waitcnt lgkmcnt(6)
	v_cvt_pk_bf16_f32 v2, v8, v6
	s_waitcnt lgkmcnt(4)
	v_cvt_pk_bf16_f32 v3, v10, v12
	s_waitcnt lgkmcnt(2)
	v_cvt_pk_bf16_f32 v4, v14, v16
	s_waitcnt lgkmcnt(0)
	v_cvt_pk_bf16_f32 v5, v18, v20
	v_lshl_add_u64 v[50:51], v[48:49], 0, v[50:51]
	v_add_u32_e32 v6, s8, v43
	global_store_dwordx4 v[50:51], v[2:5], off
	s_nop 1
	v_cvt_pk_bf16_f32 v2, v9, v7
	v_ashrrev_i32_e32 v7, 31, v6
	v_cvt_pk_bf16_f32 v3, v11, v13
	v_cvt_pk_bf16_f32 v4, v15, v17
	v_cvt_pk_bf16_f32 v5, v19, v21
	v_lshlrev_b64 v[6:7], 9, v[6:7]
	ds_read2_b32 v[8:9], v41 offset0:49 offset1:57
	ds_read2_b32 v[10:11], v41 offset0:16 offset1:24
	ds_read2_b32 v[12:13], v41 offset0:82 offset1:90
	ds_read2_b32 v[14:15], v41 offset0:115 offset1:123
	ds_read2_b32 v[16:17], v41 offset0:148 offset1:156
	ds_read2_b32 v[18:19], v41 offset0:181 offset1:189
	ds_read2_b32 v[20:21], v41 offset0:214 offset1:222
	ds_read2_b32 v[50:51], v41 offset0:247 offset1:255
	v_lshl_add_u64 v[6:7], v[48:49], 0, v[6:7]
	global_store_dwordx4 v[6:7], v[2:5], off
	v_add_u32_e32 v6, s8, v45
	v_ashrrev_i32_e32 v7, 31, v6
	v_lshlrev_b64 v[6:7], 9, v[6:7]
	s_waitcnt lgkmcnt(6)
	v_cvt_pk_bf16_f32 v2, v10, v8
	s_waitcnt lgkmcnt(4)
	v_cvt_pk_bf16_f32 v3, v12, v14
	s_waitcnt lgkmcnt(2)
	v_cvt_pk_bf16_f32 v4, v16, v18
	s_waitcnt lgkmcnt(0)
	v_cvt_pk_bf16_f32 v5, v20, v50
	v_lshl_add_u64 v[6:7], v[48:49], 0, v[6:7]
	global_store_dwordx4 v[6:7], v[2:5], off
	v_add_u32_e32 v6, s8, v58
	v_ashrrev_i32_e32 v7, 31, v6
	v_lshlrev_b64 v[6:7], 9, v[6:7]
	v_cvt_pk_bf16_f32 v2, v11, v9
	v_cvt_pk_bf16_f32 v3, v13, v15
	v_cvt_pk_bf16_f32 v4, v17, v19
	v_cvt_pk_bf16_f32 v5, v21, v51
	v_lshl_add_u64 v[6:7], v[48:49], 0, v[6:7]
	global_store_dwordx4 v[6:7], v[2:5], off
	s_waitcnt lgkmcnt(0)

.LBB0_42:
	s_lshl_b32 s20, s11, 1
	s_lshl_b32 s21, s10, 1
	v_add_u32_e32 v20, s20, v4
	v_add_u32_e32 v48, s21, v5
	v_add_u32_e32 v50, s20, v6
	v_add_u32_e32 v52, s21, v7
	v_add_u32_e32 v54, s20, v8
	v_add_u32_e32 v56, s21, v9
	v_add_u32_e32 v60, s20, v10
	v_add_u32_e32 v62, s21, v11
	v_add_u32_e32 v64, s20, v12
	v_add_u32_e32 v68, s21, v13
	v_add_u32_e32 v70, s20, v14
	v_add_u32_e32 v72, s21, v15
	v_add_u32_e32 v74, s20, v16
	v_add_u32_e32 v76, s21, v17
	v_add_u32_e32 v78, s20, v18
	v_add_u32_e32 v80, s21, v19
	v_ashrrev_i32_e32 v21, 31, v20
	v_ashrrev_i32_e32 v49, 31, v48
	v_ashrrev_i32_e32 v51, 31, v50
	v_ashrrev_i32_e32 v53, 31, v52
	v_ashrrev_i32_e32 v55, 31, v54
	v_ashrrev_i32_e32 v57, 31, v56
	v_ashrrev_i32_e32 v61, 31, v60
	v_ashrrev_i32_e32 v63, 31, v62
	v_ashrrev_i32_e32 v65, 31, v64
	v_ashrrev_i32_e32 v69, 31, v68
	v_ashrrev_i32_e32 v71, 31, v70
	v_ashrrev_i32_e32 v73, 31, v72
	v_ashrrev_i32_e32 v75, 31, v74
	v_ashrrev_i32_e32 v77, 31, v76
	v_ashrrev_i32_e32 v79, 31, v78
	v_ashrrev_i32_e32 v81, 31, v80
	v_lshlrev_b64 v[20:21], 12, v[20:21]
	v_lshlrev_b64 v[48:49], 12, v[48:49]
	v_lshlrev_b64 v[50:51], 12, v[50:51]
	v_lshlrev_b64 v[52:53], 12, v[52:53]
	v_lshlrev_b64 v[54:55], 12, v[54:55]
	v_lshlrev_b64 v[56:57], 12, v[56:57]
	v_lshlrev_b64 v[60:61], 12, v[60:61]
	v_lshlrev_b64 v[62:63], 12, v[62:63]
	v_lshlrev_b64 v[64:65], 12, v[64:65]
	v_lshlrev_b64 v[68:69], 12, v[68:69]
	v_lshlrev_b64 v[70:71], 12, v[70:71]
	v_lshlrev_b64 v[72:73], 12, v[72:73]
	v_lshlrev_b64 v[74:75], 12, v[74:75]
	v_lshlrev_b64 v[76:77], 12, v[76:77]
	v_lshlrev_b64 v[78:79], 12, v[78:79]
	v_lshlrev_b64 v[80:81], 12, v[80:81]
	v_lshl_add_u64 v[20:21], v[2:3], 0, v[20:21]
	v_lshl_add_u64 v[48:49], v[2:3], 0, v[48:49]
	v_lshl_add_u64 v[50:51], v[2:3], 0, v[50:51]
	v_lshl_add_u64 v[52:53], v[2:3], 0, v[52:53]
	v_lshl_add_u64 v[54:55], v[2:3], 0, v[54:55]
	v_lshl_add_u64 v[56:57], v[2:3], 0, v[56:57]
	v_lshl_add_u64 v[60:61], v[2:3], 0, v[60:61]
	v_lshl_add_u64 v[62:63], v[2:3], 0, v[62:63]
	v_lshl_add_u64 v[64:65], v[2:3], 0, v[64:65]
	v_lshl_add_u64 v[68:69], v[2:3], 0, v[68:69]
	v_lshl_add_u64 v[70:71], v[2:3], 0, v[70:71]
	v_lshl_add_u64 v[72:73], v[2:3], 0, v[72:73]
	v_lshl_add_u64 v[74:75], v[2:3], 0, v[74:75]
	v_lshl_add_u64 v[76:77], v[2:3], 0, v[76:77]
	v_lshl_add_u64 v[78:79], v[2:3], 0, v[78:79]
	v_lshl_add_u64 v[80:81], v[2:3], 0, v[80:81]
	global_load_dword v24, v[20:21], off nt
	global_load_dword v47, v[48:49], off nt
	global_load_dword v59, v[50:51], off nt
	global_load_dword v67, v[52:53], off nt
	global_load_dword v82, v[54:55], off nt
	global_load_dword v83, v[56:57], off nt
	global_load_dword v84, v[60:61], off nt
	global_load_dword v85, v[62:63], off nt
	global_load_dword v86, v[64:65], off nt
	global_load_dword v87, v[68:69], off nt
	global_load_dword v88, v[70:71], off nt
	global_load_dword v89, v[72:73], off nt
	global_load_dword v90, v[74:75], off nt
	global_load_dword v91, v[76:77], off nt
	global_load_dword v92, v[78:79], off nt
	global_load_dword v93, v[80:81], off nt
	s_add_i32 s11, s11, 16
	s_add_i32 s10, s10, 16
	s_add_i32 s16, s16, -16
	v_add_u32_e32 v20, s20, v22
	v_add_u32_e32 v48, s21, v1
	v_add_u32_e32 v50, s20, v32
	v_add_u32_e32 v52, s21, v23
	v_add_u32_e32 v54, s20, v34
	v_add_u32_e32 v56, s21, v27
	v_add_u32_e32 v60, s20, v36
	v_add_u32_e32 v62, s21, v29
	v_add_u32_e32 v64, s20, v38
	v_add_u32_e32 v68, s21, v33
	v_add_u32_e32 v70, s20, v40
	v_add_u32_e32 v72, s21, v35
	v_add_u32_e32 v74, s20, v42
	v_add_u32_e32 v76, s21, v37
	v_add_u32_e32 v78, s20, v44
	v_add_u32_e32 v80, s21, v39
	s_cmp_lg_u32 s16, 0
	v_mad_u64_u32 v[20:21], s[20:21], v20, s47, v[26:27]
	v_mad_u64_u32 v[48:49], s[20:21], v48, s47, v[26:27]
	v_mad_u64_u32 v[50:51], s[20:21], v50, s47, v[26:27]
	v_mad_u64_u32 v[52:53], s[20:21], v52, s47, v[26:27]
	v_mad_u64_u32 v[54:55], s[20:21], v54, s47, v[26:27]
	v_mad_u64_u32 v[56:57], s[20:21], v56, s47, v[26:27]
	v_mad_u64_u32 v[60:61], s[20:21], v60, s47, v[26:27]
	v_mad_u64_u32 v[62:63], s[20:21], v62, s47, v[26:27]
	v_mad_u64_u32 v[64:65], s[20:21], v64, s47, v[26:27]
	v_mad_u64_u32 v[68:69], s[20:21], v68, s47, v[26:27]
	v_mad_u64_u32 v[70:71], s[20:21], v70, s47, v[26:27]
	v_mad_u64_u32 v[72:73], s[20:21], v72, s47, v[26:27]
	v_mad_u64_u32 v[74:75], s[20:21], v74, s47, v[26:27]
	v_mad_u64_u32 v[76:77], s[20:21], v76, s47, v[26:27]
	v_mad_u64_u32 v[78:79], s[20:21], v78, s47, v[26:27]
	v_mad_u64_u32 v[80:81], s[20:21], v80, s47, v[26:27]
	s_waitcnt vmcnt(15)
	ds_write_b32 v20, v24
	s_waitcnt vmcnt(14)
	ds_write_b32 v48, v47
	s_waitcnt vmcnt(13)
	ds_write_b32 v50, v59
	s_waitcnt vmcnt(12)
	ds_write_b32 v52, v67
	s_waitcnt vmcnt(11)
	ds_write_b32 v54, v82
	s_waitcnt vmcnt(10)
	ds_write_b32 v56, v83
	s_waitcnt vmcnt(9)
	ds_write_b32 v60, v84
	s_waitcnt vmcnt(8)
	ds_write_b32 v62, v85
	s_waitcnt vmcnt(7)
	ds_write_b32 v64, v86
	s_waitcnt vmcnt(6)
	ds_write_b32 v68, v87
	s_waitcnt vmcnt(5)
	ds_write_b32 v70, v88
	s_waitcnt vmcnt(4)
	ds_write_b32 v72, v89
	s_waitcnt vmcnt(3)
	ds_write_b32 v74, v90
	s_waitcnt vmcnt(2)
	ds_write_b32 v76, v91
	s_waitcnt vmcnt(1)
	ds_write_b32 v78, v92
	s_waitcnt vmcnt(0)
	ds_write_b32 v80, v93
	s_cbranch_scc1 .LBB0_42
	s_lshl_b64 s[4:5], s[4:5], 1
	s_waitcnt lgkmcnt(0)
	s_add_u32 s4, s39, s4
	ds_read2_b32 v[6:7], v41 offset0:33 offset1:41
	ds_read2_b32 v[8:9], v41 offset1:8
	ds_read2_b32 v[10:11], v41 offset0:66 offset1:74
	ds_read2_b32 v[12:13], v41 offset0:99 offset1:107
	ds_read2_b32 v[14:15], v41 offset0:132 offset1:140
	ds_read2_b32 v[16:17], v41 offset0:165 offset1:173
	ds_read2_b32 v[18:19], v41 offset0:198 offset1:206
	ds_read2_b32 v[20:21], v41 offset0:231 offset1:239
	s_addc_u32 s5, s40, s5
	s_lshl_b32 s9, s9, 1
	s_add_u32 s4, s4, s9
	v_add_u32_e32 v50, s8, v30
	s_addc_u32 s5, s5, 0
	v_lshlrev_b32_e32 v24, 1, v28
	v_ashrrev_i32_e32 v51, 31, v50
	v_lshl_add_u64 v[48:49], s[4:5], 0, v[24:25]
	v_lshlrev_b64 v[50:51], 11, v[50:51]
	s_waitcnt lgkmcnt(6)
	v_cvt_pk_bf16_f32 v2, v8, v6
	s_waitcnt lgkmcnt(4)
	v_cvt_pk_bf16_f32 v3, v10, v12
	s_waitcnt lgkmcnt(2)
	v_cvt_pk_bf16_f32 v4, v14, v16
	s_waitcnt lgkmcnt(0)
	v_cvt_pk_bf16_f32 v5, v18, v20
	v_lshl_add_u64 v[50:51], v[48:49], 0, v[50:51]
	v_add_u32_e32 v6, s8, v43
	global_store_dwordx4 v[50:51], v[2:5], off
	s_nop 1
	v_cvt_pk_bf16_f32 v2, v9, v7
	v_ashrrev_i32_e32 v7, 31, v6
	v_cvt_pk_bf16_f32 v3, v11, v13
	v_cvt_pk_bf16_f32 v4, v15, v17
	v_cvt_pk_bf16_f32 v5, v19, v21
	v_lshlrev_b64 v[6:7], 11, v[6:7]
	ds_read2_b32 v[8:9], v41 offset0:49 offset1:57
	ds_read2_b32 v[10:11], v41 offset0:16 offset1:24
	ds_read2_b32 v[12:13], v41 offset0:82 offset1:90
	ds_read2_b32 v[14:15], v41 offset0:115 offset1:123
	ds_read2_b32 v[16:17], v41 offset0:148 offset1:156
	ds_read2_b32 v[18:19], v41 offset0:181 offset1:189
	ds_read2_b32 v[20:21], v41 offset0:214 offset1:222
	ds_read2_b32 v[50:51], v41 offset0:247 offset1:255
	v_lshl_add_u64 v[6:7], v[48:49], 0, v[6:7]
	global_store_dwordx4 v[6:7], v[2:5], off
	v_add_u32_e32 v6, s8, v45
	v_ashrrev_i32_e32 v7, 31, v6
	v_lshlrev_b64 v[6:7], 11, v[6:7]
	s_waitcnt lgkmcnt(6)
	v_cvt_pk_bf16_f32 v2, v10, v8
	s_waitcnt lgkmcnt(4)
	v_cvt_pk_bf16_f32 v3, v12, v14
	s_waitcnt lgkmcnt(2)
	v_cvt_pk_bf16_f32 v4, v16, v18
	s_waitcnt lgkmcnt(0)
	v_cvt_pk_bf16_f32 v5, v20, v50
	v_lshl_add_u64 v[6:7], v[48:49], 0, v[6:7]
	global_store_dwordx4 v[6:7], v[2:5], off
	v_add_u32_e32 v6, s8, v58
	v_ashrrev_i32_e32 v7, 31, v6
	v_lshlrev_b64 v[6:7], 11, v[6:7]
	v_cvt_pk_bf16_f32 v2, v11, v9
	v_cvt_pk_bf16_f32 v3, v13, v15
	v_cvt_pk_bf16_f32 v4, v17, v19
	v_cvt_pk_bf16_f32 v5, v21, v51
	v_lshl_add_u64 v[6:7], v[48:49], 0, v[6:7]
	global_store_dwordx4 v[6:7], v[2:5], off
	s_waitcnt lgkmcnt(0)

.LBB0_48:
	s_lshl_b32 s25, s16, 1
	s_lshl_b32 s53, s9, 1
	v_add_u32_e32 v20, s25, v4
	v_add_u32_e32 v24, s53, v5
	v_add_u32_e32 v47, s25, v6
	v_add_u32_e32 v52, s53, v7
	v_add_u32_e32 v54, s25, v8
	v_add_u32_e32 v56, s53, v9
	v_add_u32_e32 v59, s25, v10
	v_add_u32_e32 v62, s53, v11
	v_add_u32_e32 v64, s25, v12
	v_add_u32_e32 v67, s53, v13
	v_add_u32_e32 v70, s25, v14
	v_add_u32_e32 v72, s53, v15
	v_add_u32_e32 v74, s25, v16
	v_add_u32_e32 v76, s53, v17
	v_add_u32_e32 v78, s25, v18
	v_add_u32_e32 v80, s53, v19
	v_mad_i64_i32 v[20:21], s[54:55], v20, s50, v[2:3]
	v_mad_i64_i32 v[48:49], s[54:55], v24, s50, v[2:3]
	v_mad_i64_i32 v[50:51], s[54:55], v47, s50, v[2:3]
	v_mad_i64_i32 v[52:53], s[54:55], v52, s50, v[2:3]
	v_mad_i64_i32 v[54:55], s[54:55], v54, s50, v[2:3]
	v_mad_i64_i32 v[56:57], s[54:55], v56, s50, v[2:3]
	v_mad_i64_i32 v[60:61], s[54:55], v59, s50, v[2:3]
	v_mad_i64_i32 v[62:63], s[54:55], v62, s50, v[2:3]
	v_mad_i64_i32 v[64:65], s[54:55], v64, s50, v[2:3]
	v_mad_i64_i32 v[68:69], s[54:55], v67, s50, v[2:3]
	v_mad_i64_i32 v[70:71], s[54:55], v70, s50, v[2:3]
	v_mad_i64_i32 v[72:73], s[54:55], v72, s50, v[2:3]
	v_mad_i64_i32 v[74:75], s[54:55], v74, s50, v[2:3]
	v_mad_i64_i32 v[76:77], s[54:55], v76, s50, v[2:3]
	v_mad_i64_i32 v[78:79], s[54:55], v78, s50, v[2:3]
	v_mad_i64_i32 v[80:81], s[54:55], v80, s50, v[2:3]
	global_load_dword v24, v[20:21], off nt
	global_load_dword v47, v[48:49], off nt
	global_load_dword v59, v[50:51], off nt
	global_load_dword v67, v[52:53], off nt
	global_load_dword v82, v[54:55], off nt
	global_load_dword v83, v[56:57], off nt
	global_load_dword v84, v[60:61], off nt
	global_load_dword v85, v[62:63], off nt
	global_load_dword v86, v[64:65], off nt
	global_load_dword v87, v[68:69], off nt
	global_load_dword v88, v[70:71], off nt
	global_load_dword v89, v[72:73], off nt
	global_load_dword v90, v[74:75], off nt
	global_load_dword v91, v[76:77], off nt
	global_load_dword v92, v[78:79], off nt
	global_load_dword v93, v[80:81], off nt
	s_add_i32 s16, s16, 16
	s_add_i32 s9, s9, 16
	s_add_i32 s24, s24, -16
	v_add_u32_e32 v20, s25, v22
	v_add_u32_e32 v48, s53, v1
	v_add_u32_e32 v50, s25, v32
	v_add_u32_e32 v52, s53, v23
	v_add_u32_e32 v54, s25, v34
	v_add_u32_e32 v56, s53, v27
	v_add_u32_e32 v60, s25, v36
	v_add_u32_e32 v62, s53, v29
	v_add_u32_e32 v64, s25, v38
	v_add_u32_e32 v68, s53, v33
	v_add_u32_e32 v70, s25, v40
	v_add_u32_e32 v72, s53, v35
	v_add_u32_e32 v74, s25, v42
	v_add_u32_e32 v76, s53, v37
	v_add_u32_e32 v78, s25, v44
	v_add_u32_e32 v80, s53, v39
	s_cmp_lg_u32 s24, 0
	v_mad_u64_u32 v[20:21], s[54:55], v20, s47, v[26:27]
	v_mad_u64_u32 v[48:49], s[54:55], v48, s47, v[26:27]
	v_mad_u64_u32 v[50:51], s[54:55], v50, s47, v[26:27]
	v_mad_u64_u32 v[52:53], s[54:55], v52, s47, v[26:27]
	v_mad_u64_u32 v[54:55], s[54:55], v54, s47, v[26:27]
	v_mad_u64_u32 v[56:57], s[54:55], v56, s47, v[26:27]
	v_mad_u64_u32 v[60:61], s[54:55], v60, s47, v[26:27]
	v_mad_u64_u32 v[62:63], s[54:55], v62, s47, v[26:27]
	v_mad_u64_u32 v[64:65], s[54:55], v64, s47, v[26:27]
	v_mad_u64_u32 v[68:69], s[54:55], v68, s47, v[26:27]
	v_mad_u64_u32 v[70:71], s[54:55], v70, s47, v[26:27]
	v_mad_u64_u32 v[72:73], s[54:55], v72, s47, v[26:27]
	v_mad_u64_u32 v[74:75], s[54:55], v74, s47, v[26:27]
	v_mad_u64_u32 v[76:77], s[54:55], v76, s47, v[26:27]
	v_mad_u64_u32 v[78:79], s[54:55], v78, s47, v[26:27]
	v_mad_u64_u32 v[80:81], s[54:55], v80, s47, v[26:27]
	s_waitcnt vmcnt(15)
	ds_write_b32 v20, v24
	s_waitcnt vmcnt(14)
	ds_write_b32 v48, v47
	s_waitcnt vmcnt(13)
	ds_write_b32 v50, v59
	s_waitcnt vmcnt(12)
	ds_write_b32 v52, v67
	s_waitcnt vmcnt(11)
	ds_write_b32 v54, v82
	s_waitcnt vmcnt(10)
	ds_write_b32 v56, v83
	s_waitcnt vmcnt(9)
	ds_write_b32 v60, v84
	s_waitcnt vmcnt(8)
	ds_write_b32 v62, v85
	s_waitcnt vmcnt(7)
	ds_write_b32 v64, v86
	s_waitcnt vmcnt(6)
	ds_write_b32 v68, v87
	s_waitcnt vmcnt(5)
	ds_write_b32 v70, v88
	s_waitcnt vmcnt(4)
	ds_write_b32 v72, v89
	s_waitcnt vmcnt(3)
	ds_write_b32 v74, v90
	s_waitcnt vmcnt(2)
	ds_write_b32 v76, v91
	s_waitcnt vmcnt(1)
	ds_write_b32 v78, v92
	s_waitcnt vmcnt(0)
	ds_write_b32 v80, v93
	s_cbranch_scc1 .LBB0_48
	s_waitcnt lgkmcnt(0)
	s_cmp_lg_u64 s[20:21], 0
	s_cselect_b64 s[24:25], -1, 0
	s_cmp_eq_u64 s[20:21], 0
	s_cbranch_scc1 .LBB0_51
	v_or_b32_e32 v2, s10, v28
	v_ashrrev_i32_e32 v3, 31, v2
	v_lshlrev_b64 v[2:3], 2, v[2:3]
	v_lshl_add_u64 v[4:5], s[20:21], 0, v[2:3]
	v_lshl_add_u64 v[2:3], s[22:23], 0, v[2:3]
	v_lshl_add_u64 v[6:7], v[2:3], 0, s[18:19]
	v_add_co_u32_e32 v2, vcc, s51, v2
	global_load_dwordx4 v[10:13], v[4:5], off offset:16
	global_load_dwordx4 v[14:17], v[4:5], off
	v_addc_co_u32_e32 v3, vcc, 0, v3, vcc
	global_load_dwordx4 v[2:5], v[2:3], off
	s_nop 0
	global_load_dwordx4 v[6:9], v[6:7], off offset:16
	s_branch .LBB0_52

.LBB0_699:
	s_mov_b32 s4, s87
	s_mov_b32 s5, s48
	v_mbcnt_lo_u32_b32 v217, -1, 0
	v_mbcnt_hi_u32_b32 v217, -1, v217
	s_lshl_b32 s19, s22, 8
	s_lshl_b32 s4, s4, 6
	v_and_b32_e32 v136, 15, v217
	s_add_i32 s19, s4, s19
	s_lshl_b32 s5, s5, 5
	v_ashrrev_i32_e32 v48, 1, v217
	s_lshl_b32 s8, s8, 8
	v_or_b32_e32 v216, s19, v136
	v_and_b32_e32 v48, -8, v48
	s_add_i32 s5, s5, s8
	v_lshlrev_b32_e32 v51, 11, v216
	v_add_u32_e32 v48, s5, v48
	v_lshl_add_u32 v160, v48, 1, v51
	v_add_u32_e32 v212, 0x8000, v160
	v_add_u32_e32 v208, 0x18000, v160
	v_add_u32_e32 v204, 0x48000, v160
	v_add_u32_e32 v210, 0x10000, v160
	global_load_dwordx4 v[182:185], v212, s[54:55] nt
	global_load_dwordx4 v[178:181], v210, s[54:55] nt
	v_add_u32_e32 v206, 0x40000, v160
	global_load_dwordx4 v[170:173], v208, s[54:55] nt
	global_load_dwordx4 v[162:165], v206, s[54:55] nt
	v_add_u32_e32 v202, 0x50000, v160
	global_load_dwordx4 v[148:151], v204, s[54:55] nt
	global_load_dwordx4 v[132:135], v202, s[54:55] nt
	v_add_u32_e32 v200, 0x58000, v160
	global_load_dwordx4 v[186:189], v160, s[54:55] nt
	global_load_dwordx4 v[120:123], v200, s[54:55] nt
	v_ashrrev_i32_e32 v49, 31, v48
	v_cndmask_b32_e64 v124, 0, 1, s[70:71]
	v_mov_b32_e32 v50, 1.0
	v_cmp_ne_u32_e64 s[42:43], 1, v124
	s_andn2_b64 vcc, exec, s[70:71]
	v_lshl_add_u64 v[198:199], v[48:49], 2, s[6:7]
	v_mov_b32_e32 v126, 1.0
	v_mov_b32_e32 v127, 1.0
	v_mov_b32_e32 v124, 1.0
	v_mov_b32_e32 v125, 1.0
	v_mov_b32_e32 v130, 1.0
	v_mov_b32_e32 v131, 1.0
	v_mov_b32_e32 v128, 1.0
	v_mov_b32_e32 v129, 1.0
	s_movk_i32 s94, 0x3000
	s_movk_i32 s81, 0x5000
	s_cbranch_vccnz .LBB0_701
	global_load_dwordx4 v[124:127], v[198:199], off offset:16
	global_load_dwordx4 v[128:131], v[198:199], off
.LBB0_701:
	v_lshlrev_b64 v[140:141], 2, v[48:49]
	v_lshl_add_u64 v[194:195], s[56:57], 0, v[140:141]
	v_or_b32_e32 v190, s4, v136
	global_load_dwordx4 v[136:139], v[194:195], off offset:16
	global_load_dwordx4 v[144:147], v[194:195], off
	v_lshl_add_u64 v[196:197], s[58:59], 0, v[140:141]
	global_load_dwordx4 v[140:143], v[196:197], off offset:16
	global_load_dwordx4 v[152:155], v[196:197], off
	s_lshl_b32 s5, s9, 11
	s_and_b32 s5, s5, 0x800
	s_add_i32 s5, s5, 0
	s_add_i32 s5, s5, 0x21000
	v_lshlrev_b32_e32 v49, 3, v190
	v_add_u32_e32 v218, s5, v49
	ds_read2_b64 v[220:223], v218 offset1:16
	s_waitcnt vmcnt(0)
	v_lshlrev_b32_e32 v224, 16, v186
	v_and_b32_e32 v225, 0xffff0000, v186
	v_pk_mul_f32 v[174:175], v[174:175], v[128:129]
	v_lshlrev_b32_e32 v186, 16, v187
	s_waitcnt lgkmcnt(0)
	v_pk_mul_f32 v[190:191], v[220:221], s[96:97] op_sel_hi:[1,0]
	v_and_b32_e32 v187, 0xffff0000, v187
	v_fma_f32 v49, -v190, v190, v191
	v_max_f32_e32 v49, 0, v49
	v_add_f32_e32 v49, 0x3727c5ac, v49
	v_rsq_f32_e32 v220, v49
	v_pk_mul_f32 v[176:177], v[176:177], v[130:131]
	v_pk_mul_f32 v[166:167], v[166:167], v[124:125]
	v_pk_mul_f32 v[168:169], v[168:169], v[126:127]
	v_pk_mul_f32 v[156:157], v[156:157], v[128:129]
	v_pk_mul_f32 v[158:159], v[158:159], v[130:131]
	v_pk_mul_f32 v[116:117], v[116:117], v[124:125]
	v_pk_mul_f32 v[118:119], v[118:119], v[126:127]
	v_mov_b32_e32 v213, v161
	v_pk_mul_f32 v[112:113], v[112:113], v[128:129]
	v_pk_mul_f32 v[114:115], v[114:115], v[130:131]
	v_pk_mul_f32 v[108:109], v[108:109], v[124:125]
	v_pk_mul_f32 v[110:111], v[110:111], v[126:127]
	v_mov_b32_e32 v211, v161
	v_pk_mul_f32 v[104:105], v[104:105], v[128:129]
	v_pk_mul_f32 v[106:107], v[106:107], v[130:131]
	v_pk_mul_f32 v[100:101], v[100:101], v[124:125]
	v_pk_mul_f32 v[102:103], v[102:103], v[126:127]
	v_mov_b32_e32 v209, v161
	v_pk_mul_f32 v[96:97], v[96:97], v[128:129]
	v_pk_mul_f32 v[98:99], v[98:99], v[130:131]
	v_pk_mul_f32 v[92:93], v[92:93], v[124:125]
	v_pk_mul_f32 v[94:95], v[94:95], v[126:127]
	v_mov_b32_e32 v207, v161
	v_pk_mul_f32 v[88:89], v[88:89], v[128:129]
	v_pk_mul_f32 v[90:91], v[90:91], v[130:131]
	v_pk_mul_f32 v[84:85], v[84:85], v[124:125]
	v_pk_mul_f32 v[86:87], v[86:87], v[126:127]
	v_mov_b32_e32 v205, v161
	v_pk_mul_f32 v[80:81], v[80:81], v[128:129]
	v_pk_mul_f32 v[82:83], v[82:83], v[130:131]
	v_pk_mul_f32 v[76:77], v[76:77], v[124:125]
	v_pk_mul_f32 v[78:79], v[78:79], v[126:127]
	v_mov_b32_e32 v203, v161
	v_pk_mul_f32 v[72:73], v[72:73], v[128:129]
	v_pk_mul_f32 v[74:75], v[74:75], v[130:131]
	v_pk_mul_f32 v[68:69], v[68:69], v[124:125]
	v_pk_mul_f32 v[70:71], v[70:71], v[126:127]
	v_mov_b32_e32 v201, v161
	v_lshl_add_u32 v48, v48, 1, v51
	s_and_b64 vcc, exec, s[42:43]
	v_mov_b32_e32 v51, 1.0
	v_pk_mul_f32 v[226:227], v[144:145], v[220:221] op_sel_hi:[1,0]
	s_nop 0
	v_pk_fma_f32 v[228:229], v[190:191], v[226:227], v[152:153] op_sel_hi:[0,1,1] neg_lo:[1,0,0] neg_hi:[1,0,0]
	v_pk_fma_f32 v[224:225], v[224:225], v[226:227], v[228:229]
	s_nop 0
	v_pk_fma_f32 v[174:175], v[224:225], s[12:13], v[174:175] op_sel_hi:[1,0,1]
	v_pk_mul_f32 v[224:225], v[146:147], v[220:221] op_sel_hi:[1,0]
	s_nop 0
	v_pk_fma_f32 v[226:227], v[190:191], v[224:225], v[154:155] op_sel_hi:[0,1,1] neg_lo:[1,0,0] neg_hi:[1,0,0]
	v_pk_fma_f32 v[186:187], v[186:187], v[224:225], v[226:227]
	v_pk_mul_f32 v[224:225], v[136:137], v[220:221] op_sel_hi:[1,0]
	v_pk_fma_f32 v[176:177], v[186:187], s[12:13], v[176:177] op_sel_hi:[1,0,1]
	v_lshlrev_b32_e32 v186, 16, v188
	v_and_b32_e32 v187, 0xffff0000, v188
	v_pk_fma_f32 v[226:227], v[190:191], v[224:225], v[140:141] op_sel_hi:[0,1,1] neg_lo:[1,0,0] neg_hi:[1,0,0]
	v_pk_fma_f32 v[186:187], v[186:187], v[224:225], v[226:227]
	s_nop 0
	v_pk_fma_f32 v[186:187], v[186:187], s[12:13], v[166:167] op_sel_hi:[1,0,1]
	v_lshlrev_b32_e32 v166, 16, v189
	v_and_b32_e32 v167, 0xffff0000, v189
	v_pk_mul_f32 v[188:189], v[138:139], v[220:221] op_sel_hi:[1,0]
	s_nop 0
	v_pk_fma_f32 v[190:191], v[190:191], v[188:189], v[142:143] op_sel_hi:[0,1,1] neg_lo:[1,0,0] neg_hi:[1,0,0]
	v_pk_fma_f32 v[166:167], v[166:167], v[188:189], v[190:191]
	s_nop 0
	v_pk_fma_f32 v[188:189], v[166:167], s[12:13], v[168:169] op_sel_hi:[1,0,1]
	v_cvt_pk_bf16_f32 v166, v174, v175
	v_cvt_pk_bf16_f32 v167, v176, v177
	v_cvt_pk_bf16_f32 v168, v186, v187
	v_cvt_pk_bf16_f32 v169, v188, v189
	v_lshl_add_u64 v[174:175], s[60:61], 0, v[160:161]
	global_store_dwordx4 v[174:175], v[166:169], off
	v_pk_mul_f32 v[174:175], v[222:223], s[96:97] op_sel_hi:[1,0]
	v_lshlrev_b32_e32 v186, 16, v182
	v_fma_f32 v49, -v174, v174, v175
	v_max_f32_e32 v49, 0, v49
	v_add_f32_e32 v49, 0x3727c5ac, v49
	v_rsq_f32_e32 v176, v49
	v_and_b32_e32 v187, 0xffff0000, v182
	v_lshlrev_b32_e32 v182, 16, v183
	v_and_b32_e32 v183, 0xffff0000, v183
	v_pk_mul_f32 v[188:189], v[144:145], v[176:177] op_sel_hi:[1,0]
	s_nop 0
	v_pk_fma_f32 v[190:191], v[174:175], v[188:189], v[152:153] op_sel_hi:[0,1,1] neg_lo:[1,0,0] neg_hi:[1,0,0]
	v_pk_fma_f32 v[186:187], v[186:187], v[188:189], v[190:191]
	s_nop 0
	v_pk_fma_f32 v[156:157], v[186:187], s[12:13], v[156:157] op_sel_hi:[1,0,1]
	v_pk_mul_f32 v[186:187], v[146:147], v[176:177] op_sel_hi:[1,0]
	s_nop 0
	v_pk_fma_f32 v[188:189], v[174:175], v[186:187], v[154:155] op_sel_hi:[0,1,1] neg_lo:[1,0,0] neg_hi:[1,0,0]
	v_pk_fma_f32 v[182:183], v[182:183], v[186:187], v[188:189]
	v_pk_mul_f32 v[186:187], v[136:137], v[176:177] op_sel_hi:[1,0]
	v_pk_fma_f32 v[158:159], v[182:183], s[12:13], v[158:159] op_sel_hi:[1,0,1]
	v_lshlrev_b32_e32 v182, 16, v184
	v_and_b32_e32 v183, 0xffff0000, v184
	v_pk_fma_f32 v[188:189], v[174:175], v[186:187], v[140:141] op_sel_hi:[0,1,1] neg_lo:[1,0,0] neg_hi:[1,0,0]
	v_pk_fma_f32 v[182:183], v[182:183], v[186:187], v[188:189]
	v_pk_mul_f32 v[176:177], v[138:139], v[176:177] op_sel_hi:[1,0]
	v_pk_fma_f32 v[182:183], v[182:183], s[12:13], v[116:117] op_sel_hi:[1,0,1]
	v_lshlrev_b32_e32 v116, 16, v185
	v_and_b32_e32 v117, 0xffff0000, v185
	v_pk_fma_f32 v[174:175], v[174:175], v[176:177], v[142:143] op_sel_hi:[0,1,1] neg_lo:[1,0,0] neg_hi:[1,0,0]
	v_pk_fma_f32 v[116:117], v[116:117], v[176:177], v[174:175]
	v_lshlrev_b32_e32 v176, 16, v178
	v_pk_fma_f32 v[174:175], v[116:117], s[12:13], v[118:119] op_sel_hi:[1,0,1]
	v_cvt_pk_bf16_f32 v116, v156, v157
	v_cvt_pk_bf16_f32 v117, v158, v159
	v_cvt_pk_bf16_f32 v118, v182, v183
	v_cvt_pk_bf16_f32 v119, v174, v175
	v_lshl_add_u64 v[156:157], s[60:61], 0, v[212:213]
	global_store_dwordx4 v[156:157], v[116:119], off
	ds_read2_b64 v[156:159], v218 offset0:32 offset1:48
	v_and_b32_e32 v177, 0xffff0000, v178
	s_waitcnt lgkmcnt(0)
	v_pk_mul_f32 v[156:157], v[156:157], s[96:97] op_sel_hi:[1,0]
	s_nop 0
	v_fma_f32 v49, -v156, v156, v157
	v_max_f32_e32 v49, 0, v49
	v_add_f32_e32 v49, 0x3727c5ac, v49
	v_rsq_f32_e32 v174, v49
	s_nop 0
	v_pk_mul_f32 v[182:183], v[144:145], v[174:175] op_sel_hi:[1,0]
	s_nop 0
	v_pk_fma_f32 v[184:185], v[156:157], v[182:183], v[152:153] op_sel_hi:[0,1,1] neg_lo:[1,0,0] neg_hi:[1,0,0]
	v_pk_fma_f32 v[176:177], v[176:177], v[182:183], v[184:185]
	s_nop 0
	v_pk_fma_f32 v[112:113], v[176:177], s[12:13], v[112:113] op_sel_hi:[1,0,1]
	v_lshlrev_b32_e32 v176, 16, v179
	v_and_b32_e32 v177, 0xffff0000, v179
	v_pk_mul_f32 v[178:179], v[146:147], v[174:175] op_sel_hi:[1,0]
	v_cvt_pk_bf16_f32 v112, v112, v113
	v_pk_fma_f32 v[182:183], v[156:157], v[178:179], v[154:155] op_sel_hi:[0,1,1] neg_lo:[1,0,0] neg_hi:[1,0,0]
	v_pk_fma_f32 v[176:177], v[176:177], v[178:179], v[182:183]
	v_pk_mul_f32 v[178:179], v[136:137], v[174:175] op_sel_hi:[1,0]
	v_pk_fma_f32 v[114:115], v[176:177], s[12:13], v[114:115] op_sel_hi:[1,0,1]
	v_lshlrev_b32_e32 v176, 16, v180
	v_and_b32_e32 v177, 0xffff0000, v180
	v_pk_fma_f32 v[182:183], v[156:157], v[178:179], v[140:141] op_sel_hi:[0,1,1] neg_lo:[1,0,0] neg_hi:[1,0,0]
	v_pk_fma_f32 v[176:177], v[176:177], v[178:179], v[182:183]
	v_pk_mul_f32 v[174:175], v[138:139], v[174:175] op_sel_hi:[1,0]
	v_pk_fma_f32 v[108:109], v[176:177], s[12:13], v[108:109] op_sel_hi:[1,0,1]
	v_lshlrev_b32_e32 v176, 16, v181
	v_and_b32_e32 v177, 0xffff0000, v181
	v_pk_fma_f32 v[156:157], v[156:157], v[174:175], v[142:143] op_sel_hi:[0,1,1] neg_lo:[1,0,0] neg_hi:[1,0,0]
	v_pk_fma_f32 v[156:157], v[176:177], v[174:175], v[156:157]
	v_cvt_pk_bf16_f32 v113, v114, v115
	v_pk_fma_f32 v[110:111], v[156:157], s[12:13], v[110:111] op_sel_hi:[1,0,1]
	v_cvt_pk_bf16_f32 v114, v108, v109
	v_cvt_pk_bf16_f32 v115, v110, v111
	v_lshl_add_u64 v[108:109], s[60:61], 0, v[210:211]
	global_store_dwordx4 v[108:109], v[112:115], off
	v_pk_mul_f32 v[108:109], v[158:159], s[96:97] op_sel_hi:[1,0]
	v_lshlrev_b32_e32 v156, 16, v170
	v_fma_f32 v49, -v108, v108, v109
	v_max_f32_e32 v49, 0, v49
	v_add_f32_e32 v49, 0x3727c5ac, v49
	v_rsq_f32_e32 v110, v49
	v_and_b32_e32 v157, 0xffff0000, v170
	v_pk_mul_f32 v[158:159], v[144:145], v[110:111] op_sel_hi:[1,0]
	s_nop 0
	v_pk_fma_f32 v[174:175], v[108:109], v[158:159], v[152:153] op_sel_hi:[0,1,1] neg_lo:[1,0,0] neg_hi:[1,0,0]
	v_pk_fma_f32 v[156:157], v[156:157], v[158:159], v[174:175]
	v_pk_mul_f32 v[158:159], v[146:147], v[110:111] op_sel_hi:[1,0]
	v_pk_fma_f32 v[104:105], v[156:157], s[12:13], v[104:105] op_sel_hi:[1,0,1]
	v_lshlrev_b32_e32 v156, 16, v171
	v_and_b32_e32 v157, 0xffff0000, v171
	v_pk_fma_f32 v[170:171], v[108:109], v[158:159], v[154:155] op_sel_hi:[0,1,1] neg_lo:[1,0,0] neg_hi:[1,0,0]
	v_pk_fma_f32 v[156:157], v[156:157], v[158:159], v[170:171]
	v_pk_mul_f32 v[158:159], v[136:137], v[110:111] op_sel_hi:[1,0]
	v_pk_fma_f32 v[106:107], v[156:157], s[12:13], v[106:107] op_sel_hi:[1,0,1]
	v_lshlrev_b32_e32 v156, 16, v172
	v_and_b32_e32 v157, 0xffff0000, v172
	v_pk_fma_f32 v[170:171], v[108:109], v[158:159], v[140:141] op_sel_hi:[0,1,1] neg_lo:[1,0,0] neg_hi:[1,0,0]
	v_pk_fma_f32 v[156:157], v[156:157], v[158:159], v[170:171]
	v_pk_mul_f32 v[110:111], v[138:139], v[110:111] op_sel_hi:[1,0]
	v_pk_fma_f32 v[156:157], v[156:157], s[12:13], v[100:101] op_sel_hi:[1,0,1]
	v_lshlrev_b32_e32 v100, 16, v173
	v_and_b32_e32 v101, 0xffff0000, v173
	v_pk_fma_f32 v[108:109], v[108:109], v[110:111], v[142:143] op_sel_hi:[0,1,1] neg_lo:[1,0,0] neg_hi:[1,0,0]
	v_pk_fma_f32 v[100:101], v[100:101], v[110:111], v[108:109]
	v_lshlrev_b32_e32 v110, 16, v162
	v_pk_fma_f32 v[108:109], v[100:101], s[12:13], v[102:103] op_sel_hi:[1,0,1]
	v_cvt_pk_bf16_f32 v100, v104, v105
	v_cvt_pk_bf16_f32 v101, v106, v107
	v_cvt_pk_bf16_f32 v102, v156, v157
	v_cvt_pk_bf16_f32 v103, v108, v109
	v_lshl_add_u64 v[104:105], s[60:61], 0, v[208:209]
	global_store_dwordx4 v[104:105], v[100:103], off
	ds_read2_b64 v[104:107], v218 offset0:128 offset1:144
	v_and_b32_e32 v111, 0xffff0000, v162
	s_waitcnt lgkmcnt(0)
	v_pk_mul_f32 v[104:105], v[104:105], s[96:97] op_sel_hi:[1,0]
	s_nop 0
	v_fma_f32 v49, -v104, v104, v105
	v_max_f32_e32 v49, 0, v49
	v_add_f32_e32 v49, 0x3727c5ac, v49
	v_rsq_f32_e32 v108, v49
	s_nop 0
	v_pk_mul_f32 v[156:157], v[144:145], v[108:109] op_sel_hi:[1,0]
	s_nop 0
	v_pk_fma_f32 v[158:159], v[104:105], v[156:157], v[152:153] op_sel_hi:[0,1,1] neg_lo:[1,0,0] neg_hi:[1,0,0]
	v_pk_fma_f32 v[110:111], v[110:111], v[156:157], v[158:159]
	v_pk_mul_f32 v[156:157], v[146:147], v[108:109] op_sel_hi:[1,0]
	v_pk_fma_f32 v[96:97], v[110:111], s[12:13], v[96:97] op_sel_hi:[1,0,1]
	v_lshlrev_b32_e32 v110, 16, v163
	v_and_b32_e32 v111, 0xffff0000, v163
	v_pk_fma_f32 v[158:159], v[104:105], v[156:157], v[154:155] op_sel_hi:[0,1,1] neg_lo:[1,0,0] neg_hi:[1,0,0]
	v_pk_fma_f32 v[110:111], v[110:111], v[156:157], v[158:159]
	v_pk_mul_f32 v[156:157], v[136:137], v[108:109] op_sel_hi:[1,0]
	v_pk_fma_f32 v[98:99], v[110:111], s[12:13], v[98:99] op_sel_hi:[1,0,1]
	v_lshlrev_b32_e32 v110, 16, v164
	v_and_b32_e32 v111, 0xffff0000, v164
	v_pk_fma_f32 v[158:159], v[104:105], v[156:157], v[140:141] op_sel_hi:[0,1,1] neg_lo:[1,0,0] neg_hi:[1,0,0]
	v_pk_fma_f32 v[110:111], v[110:111], v[156:157], v[158:159]
	v_pk_mul_f32 v[108:109], v[138:139], v[108:109] op_sel_hi:[1,0]
	v_pk_fma_f32 v[110:111], v[110:111], s[12:13], v[92:93] op_sel_hi:[1,0,1]
	v_lshlrev_b32_e32 v92, 16, v165
	v_and_b32_e32 v93, 0xffff0000, v165
	v_pk_fma_f32 v[104:105], v[104:105], v[108:109], v[142:143] op_sel_hi:[0,1,1] neg_lo:[1,0,0] neg_hi:[1,0,0]
	v_pk_fma_f32 v[92:93], v[92:93], v[108:109], v[104:105]
	s_nop 0
	v_pk_fma_f32 v[104:105], v[92:93], s[12:13], v[94:95] op_sel_hi:[1,0,1]
	v_cvt_pk_bf16_f32 v92, v96, v97
	v_cvt_pk_bf16_f32 v93, v98, v99
	v_cvt_pk_bf16_f32 v94, v110, v111
	v_cvt_pk_bf16_f32 v95, v104, v105
	v_lshl_add_u64 v[96:97], s[60:61], 0, v[206:207]
	global_store_dwordx4 v[96:97], v[92:95], off
	v_pk_mul_f32 v[96:97], v[106:107], s[96:97] op_sel_hi:[1,0]
	v_lshlrev_b32_e32 v104, 16, v148
	v_fma_f32 v49, -v96, v96, v97
	v_max_f32_e32 v49, 0, v49
	v_add_f32_e32 v49, 0x3727c5ac, v49
	v_rsq_f32_e32 v98, v49
	v_and_b32_e32 v105, 0xffff0000, v148
	v_pk_mul_f32 v[106:107], v[144:145], v[98:99] op_sel_hi:[1,0]
	s_nop 0
	v_pk_fma_f32 v[108:109], v[96:97], v[106:107], v[152:153] op_sel_hi:[0,1,1] neg_lo:[1,0,0] neg_hi:[1,0,0]
	v_pk_fma_f32 v[104:105], v[104:105], v[106:107], v[108:109]
	v_pk_mul_f32 v[106:107], v[146:147], v[98:99] op_sel_hi:[1,0]
	v_pk_fma_f32 v[88:89], v[104:105], s[12:13], v[88:89] op_sel_hi:[1,0,1]
	v_lshlrev_b32_e32 v104, 16, v149
	v_and_b32_e32 v105, 0xffff0000, v149
	v_pk_fma_f32 v[108:109], v[96:97], v[106:107], v[154:155] op_sel_hi:[0,1,1] neg_lo:[1,0,0] neg_hi:[1,0,0]
	v_pk_fma_f32 v[104:105], v[104:105], v[106:107], v[108:109]
	v_pk_mul_f32 v[106:107], v[136:137], v[98:99] op_sel_hi:[1,0]
	v_pk_fma_f32 v[90:91], v[104:105], s[12:13], v[90:91] op_sel_hi:[1,0,1]
	v_lshlrev_b32_e32 v104, 16, v150
	v_and_b32_e32 v105, 0xffff0000, v150
	v_pk_fma_f32 v[108:109], v[96:97], v[106:107], v[140:141] op_sel_hi:[0,1,1] neg_lo:[1,0,0] neg_hi:[1,0,0]
	v_pk_fma_f32 v[104:105], v[104:105], v[106:107], v[108:109]
	v_pk_mul_f32 v[98:99], v[138:139], v[98:99] op_sel_hi:[1,0]
	v_pk_fma_f32 v[84:85], v[104:105], s[12:13], v[84:85] op_sel_hi:[1,0,1]
	v_lshlrev_b32_e32 v104, 16, v151
	v_and_b32_e32 v105, 0xffff0000, v151
	v_pk_fma_f32 v[96:97], v[96:97], v[98:99], v[142:143] op_sel_hi:[0,1,1] neg_lo:[1,0,0] neg_hi:[1,0,0]
	v_pk_fma_f32 v[96:97], v[104:105], v[98:99], v[96:97]
	v_cvt_pk_bf16_f32 v148, v88, v89
	v_pk_fma_f32 v[86:87], v[96:97], s[12:13], v[86:87] op_sel_hi:[1,0,1]
	v_cvt_pk_bf16_f32 v149, v90, v91
	v_cvt_pk_bf16_f32 v150, v84, v85
	v_cvt_pk_bf16_f32 v151, v86, v87
	v_lshl_add_u64 v[84:85], s[60:61], 0, v[204:205]
	global_store_dwordx4 v[84:85], v[148:151], off
	ds_read2_b64 v[84:87], v218 offset0:160 offset1:176
	v_lshlrev_b32_e32 v90, 16, v132
	v_and_b32_e32 v91, 0xffff0000, v132
	s_waitcnt lgkmcnt(0)
	v_pk_mul_f32 v[84:85], v[84:85], s[96:97] op_sel_hi:[1,0]
	s_nop 0
	v_fma_f32 v49, -v84, v84, v85
	v_max_f32_e32 v49, 0, v49
	v_add_f32_e32 v49, 0x3727c5ac, v49
	v_rsq_f32_e32 v88, v49
	s_nop 0
	v_pk_mul_f32 v[96:97], v[144:145], v[88:89] op_sel_hi:[1,0]
	s_nop 0
	v_pk_fma_f32 v[98:99], v[84:85], v[96:97], v[152:153] op_sel_hi:[0,1,1] neg_lo:[1,0,0] neg_hi:[1,0,0]
	v_pk_fma_f32 v[90:91], v[90:91], v[96:97], v[98:99]
	v_pk_mul_f32 v[96:97], v[146:147], v[88:89] op_sel_hi:[1,0]
	v_pk_fma_f32 v[80:81], v[90:91], s[12:13], v[80:81] op_sel_hi:[1,0,1]
	v_lshlrev_b32_e32 v90, 16, v133
	v_and_b32_e32 v91, 0xffff0000, v133
	v_pk_fma_f32 v[98:99], v[84:85], v[96:97], v[154:155] op_sel_hi:[0,1,1] neg_lo:[1,0,0] neg_hi:[1,0,0]
	v_pk_fma_f32 v[90:91], v[90:91], v[96:97], v[98:99]
	v_pk_mul_f32 v[96:97], v[136:137], v[88:89] op_sel_hi:[1,0]
	v_pk_fma_f32 v[82:83], v[90:91], s[12:13], v[82:83] op_sel_hi:[1,0,1]
	v_lshlrev_b32_e32 v90, 16, v134
	v_and_b32_e32 v91, 0xffff0000, v134
	v_pk_fma_f32 v[98:99], v[84:85], v[96:97], v[140:141] op_sel_hi:[0,1,1] neg_lo:[1,0,0] neg_hi:[1,0,0]
	v_pk_fma_f32 v[90:91], v[90:91], v[96:97], v[98:99]
	v_pk_mul_f32 v[88:89], v[138:139], v[88:89] op_sel_hi:[1,0]
	v_pk_fma_f32 v[76:77], v[90:91], s[12:13], v[76:77] op_sel_hi:[1,0,1]
	v_lshlrev_b32_e32 v90, 16, v135
	v_and_b32_e32 v91, 0xffff0000, v135
	v_pk_fma_f32 v[84:85], v[84:85], v[88:89], v[142:143] op_sel_hi:[0,1,1] neg_lo:[1,0,0] neg_hi:[1,0,0]
	v_pk_fma_f32 v[84:85], v[90:91], v[88:89], v[84:85]
	v_cvt_pk_bf16_f32 v132, v80, v81
	v_pk_fma_f32 v[78:79], v[84:85], s[12:13], v[78:79] op_sel_hi:[1,0,1]
	v_cvt_pk_bf16_f32 v133, v82, v83
	v_cvt_pk_bf16_f32 v134, v76, v77
	v_cvt_pk_bf16_f32 v135, v78, v79
	v_lshl_add_u64 v[76:77], s[60:61], 0, v[202:203]
	global_store_dwordx4 v[76:77], v[132:135], off
	v_pk_mul_f32 v[76:77], v[86:87], s[96:97] op_sel_hi:[1,0]
	v_lshlrev_b32_e32 v80, 16, v120
	v_fma_f32 v49, -v76, v76, v77
	v_max_f32_e32 v49, 0, v49
	v_add_f32_e32 v49, 0x3727c5ac, v49
	v_rsq_f32_e32 v78, v49
	v_and_b32_e32 v81, 0xffff0000, v120
	v_add_u32_e32 v49, 0x100, v48
	v_pk_mul_f32 v[82:83], v[144:145], v[78:79] op_sel_hi:[1,0]
	s_nop 0
	v_pk_fma_f32 v[84:85], v[76:77], v[82:83], v[152:153] op_sel_hi:[0,1,1] neg_lo:[1,0,0] neg_hi:[1,0,0]
	v_pk_fma_f32 v[80:81], v[80:81], v[82:83], v[84:85]
	v_pk_mul_f32 v[82:83], v[146:147], v[78:79] op_sel_hi:[1,0]
	v_pk_fma_f32 v[72:73], v[80:81], s[12:13], v[72:73] op_sel_hi:[1,0,1]
	v_lshlrev_b32_e32 v80, 16, v121
	v_and_b32_e32 v81, 0xffff0000, v121
	v_pk_fma_f32 v[84:85], v[76:77], v[82:83], v[154:155] op_sel_hi:[0,1,1] neg_lo:[1,0,0] neg_hi:[1,0,0]
	v_pk_fma_f32 v[80:81], v[80:81], v[82:83], v[84:85]
	v_pk_mul_f32 v[82:83], v[136:137], v[78:79] op_sel_hi:[1,0]
	v_pk_fma_f32 v[74:75], v[80:81], s[12:13], v[74:75] op_sel_hi:[1,0,1]
	v_lshlrev_b32_e32 v80, 16, v122
	v_and_b32_e32 v81, 0xffff0000, v122
	v_pk_fma_f32 v[84:85], v[76:77], v[82:83], v[140:141] op_sel_hi:[0,1,1] neg_lo:[1,0,0] neg_hi:[1,0,0]
	v_pk_fma_f32 v[80:81], v[80:81], v[82:83], v[84:85]
	v_pk_mul_f32 v[78:79], v[138:139], v[78:79] op_sel_hi:[1,0]
	v_pk_fma_f32 v[68:69], v[80:81], s[12:13], v[68:69] op_sel_hi:[1,0,1]
	v_lshlrev_b32_e32 v80, 16, v123
	v_and_b32_e32 v81, 0xffff0000, v123
	v_pk_fma_f32 v[76:77], v[76:77], v[78:79], v[142:143] op_sel_hi:[0,1,1] neg_lo:[1,0,0] neg_hi:[1,0,0]
	v_pk_fma_f32 v[76:77], v[80:81], v[78:79], v[76:77]
	v_cvt_pk_bf16_f32 v128, v72, v73
	v_pk_fma_f32 v[70:71], v[76:77], s[12:13], v[70:71] op_sel_hi:[1,0,1]
	v_cvt_pk_bf16_f32 v129, v74, v75
	v_cvt_pk_bf16_f32 v130, v68, v69
	v_cvt_pk_bf16_f32 v131, v70, v71
	v_lshl_add_u64 v[68:69], s[60:61], 0, v[200:201]
	global_store_dwordx4 v[68:69], v[128:131], off
	global_load_dwordx4 v[124:127], v49, s[54:55] nt
	v_add_u32_e32 v49, 0x8100, v48
	global_load_dwordx4 v[120:123], v49, s[54:55] nt
	v_add_u32_e32 v49, 0x10100, v48
	global_load_dwordx4 v[108:111], v49, s[54:55] nt
	v_add_u32_e32 v49, 0x18100, v48
	global_load_dwordx4 v[104:107], v49, s[54:55] nt
	v_add_u32_e32 v49, 0x40100, v48
	global_load_dwordx4 v[84:87], v49, s[54:55] nt
	v_add_u32_e32 v49, 0x48100, v48
	global_load_dwordx4 v[80:83], v49, s[54:55] nt
	v_add_u32_e32 v49, 0x50100, v48
	v_add_u32_e32 v48, 0x58100, v48
	global_load_dwordx4 v[76:79], v49, s[54:55] nt
	global_load_dwordx4 v[68:71], v48, s[54:55] nt
	v_mov_b32_e32 v48, 1.0
	v_mov_b32_e32 v49, 1.0
	v_mov_b32_e32 v74, 1.0
	v_mov_b32_e32 v75, 1.0
	v_mov_b32_e32 v72, 1.0
	v_mov_b32_e32 v73, 1.0
	s_cbranch_vccnz .LBB0_703
	global_load_dwordx4 v[48:51], v[198:199], off offset:528
	global_load_dwordx4 v[72:75], v[198:199], off offset:512

.LBB0_982:
	s_lshl_b64 s[22:23], s[88:89], 2
	s_add_u32 s22, s22, s8
	s_addc_u32 s23, s23, s9
	v_ashrrev_i32_e32 v14, 3, v87
	s_or_b32 s22, s22, s86
	v_and_b32_e32 v14, -4, v14
	s_lshl_b64 s[22:23], s[22:23], 16
	v_add_u32_e32 v14, s19, v14
	s_add_u32 s22, s18, s22
	v_ashrrev_i32_e32 v15, 31, v14
	s_addc_u32 s23, s74, s23
	v_lshlrev_b64 v[14:15], 9, v[14:15]
	v_lshl_add_u64 v[14:15], s[22:23], 0, v[14:15]
	s_lshl_b32 s92, s92, 2
	v_and_b32_e32 v30, 31, v87
	v_lshl_add_u64 v[14:15], v[14:15], 0, s[92:93]
	v_lshlrev_b32_e32 v160, 2, v30
	v_lshl_add_u64 v[14:15], v[14:15], 0, v[160:161]
	s_movk_i32 s72, 0x1000
	global_store_dword v[14:15], v16, off nt
	global_store_dword v[14:15], v17, off offset:512 nt
	global_store_dword v[14:15], v18, off offset:1024 nt
	global_store_dword v[14:15], v19, off offset:1536 nt
	v_add_co_u32_e32 v16, vcc, s72, v14
	s_movk_i32 s91, 0x4000
	s_nop 0
	v_addc_co_u32_e32 v17, vcc, 0, v15, vcc
	v_add_co_u32_e32 v18, vcc, s33, v14
	s_movk_i32 s81, 0x5000
	s_nop 0
	v_addc_co_u32_e32 v19, vcc, 0, v15, vcc
	global_store_dword v[18:19], v20, off offset:-4096 nt
	global_store_dword v[16:17], v21, off offset:512 nt
	global_store_dword v[16:17], v22, off offset:1024 nt
	global_store_dword v[16:17], v23, off offset:1536 nt
	global_store_dword v[18:19], v24, off nt
	global_store_dword v[18:19], v25, off offset:512 nt
	global_store_dword v[18:19], v26, off offset:1024 nt
	global_store_dword v[18:19], v27, off offset:1536 nt
	v_add_co_u32_e32 v16, vcc, s94, v14
	s_movk_i32 s2, 0x6000
	s_nop 0
	v_addc_co_u32_e32 v17, vcc, 0, v15, vcc
	v_add_co_u32_e32 v18, vcc, s91, v14
	s_add_i32 s85, s85, s79
	s_nop 0
	v_addc_co_u32_e32 v19, vcc, 0, v15, vcc
	global_store_dword v[18:19], v28, off offset:-4096 nt
	global_store_dword v[16:17], v29, off offset:512 nt
	global_store_dword v[16:17], v96, off offset:1024 nt
	global_store_dword v[16:17], v97, off offset:1536 nt
	global_store_dword v[18:19], v0, off nt
	global_store_dword v[18:19], v1, off offset:512 nt
	global_store_dword v[18:19], v2, off offset:1024 nt
	global_store_dword v[18:19], v3, off offset:1536 nt
	v_add_co_u32_e32 v0, vcc, s81, v14
	s_cmpk_gt_i32 s85, 0x7f
	s_nop 0
	v_addc_co_u32_e32 v1, vcc, 0, v15, vcc
	v_add_co_u32_e32 v2, vcc, s2, v14
	s_nop 1
	v_addc_co_u32_e32 v3, vcc, 0, v15, vcc
	global_store_dword v[2:3], v4, off offset:-4096 nt
	global_store_dword v[0:1], v5, off offset:512 nt
	global_store_dword v[0:1], v6, off offset:1024 nt
	global_store_dword v[0:1], v7, off offset:1536 nt
	global_store_dword v[2:3], v8, off nt
	global_store_dword v[2:3], v9, off offset:512 nt
	global_store_dword v[2:3], v10, off offset:1024 nt
	global_store_dword v[2:3], v11, off offset:1536 nt
	v_add_co_u32_e32 v0, vcc, 0x7000, v14
	s_nop 1
	v_addc_co_u32_e32 v1, vcc, 0, v15, vcc
	global_store_dword v[0:1], v12, off nt
	global_store_dword v[0:1], v13, off offset:512 nt
	global_store_dword v[0:1], v98, off offset:1024 nt
	global_store_dword v[0:1], v99, off offset:1536 nt
	s_barrier
	s_cbranch_scc1 .LBB0_1011

.LBB0_1217:
	s_mov_b32 s4, s73
	s_mov_b32 s19, s82
	v_mbcnt_lo_u32_b32 v206, -1, 0
	v_mbcnt_hi_u32_b32 v206, -1, v206
	s_lshl_b32 s22, s22, 8
	s_lshl_b32 s5, s4, 6
	v_and_b32_e32 v183, 15, v206
	s_add_i32 s4, s5, s22
	v_or_b32_e32 v205, s4, v183
	s_lshl_b32 s4, s19, 5
	v_ashrrev_i32_e32 v128, 1, v206
	s_lshl_b32 s8, s8, 8
	v_and_b32_e32 v128, -8, v128
	s_add_i32 s4, s4, s8
	v_lshlrev_b32_e32 v129, 11, v205
	v_add_u32_e32 v180, s4, v128
	v_lshl_add_u32 v160, v180, 1, v129
	v_add_u32_e32 v198, 0x8000, v160
	v_add_u32_e32 v194, 0x18000, v160
	v_add_u32_e32 v186, 0x48000, v160
	v_add_u32_e32 v196, 0x10000, v160
	global_load_dwordx4 v[170:173], v198, s[44:45] nt
	global_load_dwordx4 v[166:169], v196, s[44:45] nt
	v_add_u32_e32 v188, 0x40000, v160
	global_load_dwordx4 v[162:165], v194, s[44:45] nt
	global_load_dwordx4 v[156:159], v188, s[44:45] nt
	v_add_u32_e32 v184, 0x50000, v160
	global_load_dwordx4 v[152:155], v186, s[44:45] nt
	global_load_dwordx4 v[148:151], v184, s[44:45] nt
	v_add_u32_e32 v182, 0x58000, v160
	global_load_dwordx4 v[174:177], v160, s[44:45] nt
	global_load_dwordx4 v[128:131], v182, s[44:45] nt
	v_cndmask_b32_e64 v132, 0, 1, s[60:61]
	v_mov_b32_e32 v200, 0
	v_mov_b32_e32 v202, 1.0
	v_cmp_ne_u32_e64 s[40:41], 1, v132
	s_andn2_b64 vcc, exec, s[60:61]
	v_ashrrev_i32_e32 v181, 31, v180
	v_mov_b32_e32 v134, 1.0
	v_mov_b32_e32 v135, 1.0
	v_mov_b32_e32 v138, 0
	v_mov_b32_e32 v139, 0
	v_mov_b32_e32 v132, 1.0
	v_mov_b32_e32 v133, 1.0
	v_mov_b32_e32 v136, 0
	v_mov_b32_e32 v137, 0
	v_mov_b32_e32 v142, 1.0
	v_mov_b32_e32 v143, 1.0
	v_mov_b32_e32 v146, 0
	v_mov_b32_e32 v147, 0
	v_mov_b32_e32 v140, 1.0
	v_mov_b32_e32 v141, 1.0
	v_mov_b32_e32 v144, 0
	v_mov_b32_e32 v145, 0
	s_movk_i32 s81, 0x5000
	s_cbranch_vccnz .LBB0_1219
	v_lshlrev_b64 v[136:137], 2, v[180:181]
	v_lshl_add_u64 v[138:139], s[0:1], 0, v[136:137]
	v_lshl_add_u64 v[144:145], s[6:7], 0, v[136:137]
	global_load_dwordx4 v[132:135], v[138:139], off offset:16
	global_load_dwordx4 v[140:143], v[138:139], off
	s_nop 0
	global_load_dwordx4 v[136:139], v[144:145], off offset:16
	s_nop 0
	global_load_dwordx4 v[144:147], v[144:145], off

.LBB0_1235:
	s_nop 0
	v_pk_mul_f32 v[96:97], v[140:141], v[80:81] op_sel_hi:[1,0]
	v_lshlrev_b32_e32 v98, 16, v128
	v_and_b32_e32 v99, 0xffff0000, v128
	v_pk_fma_f32 v[100:101], v[76:77], v[96:97], v[144:145] op_sel_hi:[0,1,1] neg_lo:[1,0,0] neg_hi:[1,0,0]
	v_pk_fma_f32 v[96:97], v[98:99], v[96:97], v[100:101]
	v_lshlrev_b32_e32 v98, 16, v129
	v_pk_fma_f32 v[88:89], v[96:97], s[12:13], v[88:89] op_sel_hi:[1,0,1]
	v_pk_mul_f32 v[96:97], v[142:143], v[80:81] op_sel_hi:[1,0]
	v_and_b32_e32 v99, 0xffff0000, v129
	v_pk_fma_f32 v[100:101], v[76:77], v[96:97], v[146:147] op_sel_hi:[0,1,1] neg_lo:[1,0,0] neg_hi:[1,0,0]
	v_pk_fma_f32 v[96:97], v[98:99], v[96:97], v[100:101]
	v_lshlrev_b32_e32 v98, 16, v130
	v_pk_fma_f32 v[90:91], v[96:97], s[12:13], v[90:91] op_sel_hi:[1,0,1]
	v_pk_mul_f32 v[96:97], v[132:133], v[80:81] op_sel_hi:[1,0]
	v_and_b32_e32 v99, 0xffff0000, v130
	v_pk_fma_f32 v[100:101], v[76:77], v[96:97], v[136:137] op_sel_hi:[0,1,1] neg_lo:[1,0,0] neg_hi:[1,0,0]
	v_pk_fma_f32 v[96:97], v[98:99], v[96:97], v[100:101]
	v_pk_mul_f32 v[80:81], v[134:135], v[80:81] op_sel_hi:[1,0]
	v_pk_fma_f32 v[84:85], v[96:97], s[12:13], v[84:85] op_sel_hi:[1,0,1]
	v_lshlrev_b32_e32 v96, 16, v131
	v_and_b32_e32 v97, 0xffff0000, v131
	v_pk_fma_f32 v[76:77], v[76:77], v[80:81], v[138:139] op_sel_hi:[0,1,1] neg_lo:[1,0,0] neg_hi:[1,0,0]
	v_pk_fma_f32 v[76:77], v[96:97], v[80:81], v[76:77]
	v_mov_b32_e32 v183, v161
	v_pk_fma_f32 v[76:77], v[76:77], s[12:13], v[86:87] op_sel_hi:[1,0,1]
	v_cvt_pk_bf16_f32 v88, v88, v89
	v_cvt_pk_bf16_f32 v89, v90, v91
	v_cvt_pk_bf16_f32 v90, v84, v85
	v_cvt_pk_bf16_f32 v91, v76, v77
	v_lshl_add_u64 v[76:77], s[50:51], 0, v[182:183]
	global_store_dwordx4 v[76:77], v[88:91], off
	v_add_u32_e32 v76, 0x100, v160
	v_add_u32_e32 v77, 0x8100, v160
	global_load_dwordx4 v[140:143], v76, s[44:45] nt
	global_load_dwordx4 v[136:139], v77, s[44:45] nt
	v_add_u32_e32 v76, 0x10100, v160
	v_add_u32_e32 v77, 0x18100, v160
	global_load_dwordx4 v[132:135], v76, s[44:45] nt
	global_load_dwordx4 v[128:131], v77, s[44:45] nt
	v_add_u32_e32 v76, 0x40100, v160
	v_add_u32_e32 v77, 0x48100, v160
	global_load_dwordx4 v[124:127], v76, s[44:45] nt
	global_load_dwordx4 v[120:123], v77, s[44:45] nt
	v_add_u32_e32 v76, 0x50100, v160
	v_add_u32_e32 v77, 0x58100, v160
	global_load_dwordx4 v[116:119], v76, s[44:45] nt
	global_load_dwordx4 v[84:87], v77, s[44:45] nt
	s_and_b64 vcc, exec, s[40:41]
	v_mov_b32_e32 v79, 1.0
	v_mov_b32_e32 v83, 0
	v_mov_b32_e32 v76, 1.0
	v_mov_b32_e32 v77, 1.0
	v_mov_b32_e32 v80, 0
	v_mov_b32_e32 v81, 0
	v_mov_b32_e32 v98, 1.0
	v_mov_b32_e32 v99, 1.0
	v_mov_b32_e32 v102, 0
	v_mov_b32_e32 v103, 0
	v_mov_b32_e32 v96, 1.0
	v_mov_b32_e32 v97, 1.0
	v_mov_b32_e32 v100, 0
	v_mov_b32_e32 v101, 0
	s_cbranch_vccnz .LBB0_1237
	v_lshlrev_b64 v[80:81], 2, v[180:181]
	v_lshl_add_u64 v[82:83], s[0:1], 0, v[80:81]
	v_lshl_add_u64 v[100:101], s[6:7], 0, v[80:81]
	global_load_dwordx4 v[76:79], v[82:83], off offset:528
	global_load_dwordx4 v[96:99], v[82:83], off offset:512
	s_nop 0
	global_load_dwordx4 v[80:83], v[100:101], off offset:528
	s_nop 0
	global_load_dwordx4 v[100:103], v[100:101], off offset:512

.LBB0_1573:
	s_mov_b32 s8, s43
	s_mov_b32 s9, s77
	v_mbcnt_lo_u32_b32 v160, -1, 0
	v_mbcnt_hi_u32_b32 v160, -1, v160
	s_lshl_b32 s8, s8, 6
	v_and_b32_e32 v128, 15, v160
	s_lshl_b32 s4, s4, 8
	v_or_b32_e32 v129, s8, v128
	s_add_i32 s8, s8, s4
	v_or_b32_e32 v176, s8, v128
	s_lshl_b32 s4, s9, 5
	v_ashrrev_i32_e32 v128, 1, v160
	s_lshl_b32 s5, s5, 8
	v_and_b32_e32 v128, -8, v128
	s_add_i32 s4, s4, s5
	v_add_u32_e32 v136, s4, v128
	s_lshl_b32 s18, s18, 11
	v_lshlrev_b32_e32 v128, 1, v136
	v_ashrrev_i32_e32 v137, 31, v136
	s_and_b32 s18, s18, 0x800
	v_lshl_add_u32 v178, v176, 11, v128
	v_lshlrev_b64 v[140:141], 2, v[136:137]
	s_add_i32 s18, s18, 0
	v_add_u32_e32 v191, 0x8000, v178
	v_add_u32_e32 v200, 0x10000, v178
	v_add_u32_e32 v201, 0x18000, v178
	v_add_u32_e32 v202, 0x40000, v178
	v_add_u32_e32 v203, 0x48000, v178
	v_add_u32_e32 v204, 0x50000, v178
	v_add_u32_e32 v179, 0x58000, v178
	v_lshl_add_u64 v[170:171], s[52:53], 0, v[140:141]
	v_lshl_add_u32 v177, v129, 3, s18
	global_load_dwordx4 v[180:183], v178, s[50:51] nt
	global_load_dwordx4 v[128:131], v179, s[50:51] nt
	global_load_dwordx4 v[184:187], v191, s[50:51] nt
	global_load_dwordx4 v[166:169], v200, s[50:51] nt
	global_load_dwordx4 v[162:165], v201, s[50:51] nt
	global_load_dwordx4 v[156:159], v202, s[50:51] nt
	global_load_dwordx4 v[152:155], v203, s[50:51] nt
	global_load_dwordx4 v[132:135], v204, s[50:51] nt
	global_load_dwordx4 v[136:139], v[170:171], off offset:16
	global_load_dwordx4 v[144:147], v[170:171], off
	v_lshl_add_u64 v[172:173], s[54:55], 0, v[140:141]
	global_load_dwordx4 v[140:143], v[172:173], off offset:16
	global_load_dwordx4 v[148:151], v[172:173], off
	v_add_u32_e32 v177, 0x21000, v177
	ds_read_b64 v[188:189], v177
	v_cmp_gt_u32_e32 vcc, 16, v160
	s_waitcnt lgkmcnt(0)
	v_pk_mul_f32 v[188:189], v[188:189], s[96:97] op_sel_hi:[1,0]
	s_nop 0
	v_fma_f32 v190, -v188, v188, v189
	v_max_f32_e32 v190, 0, v190
	v_add_f32_e32 v190, 0x3727c5ac, v190
	v_rsq_f32_e32 v190, v190
	s_waitcnt vmcnt(0)
	v_lshlrev_b32_e32 v194, 16, v180
	v_and_b32_e32 v195, 0xffff0000, v180
	v_lshlrev_b32_e32 v180, 16, v181
	v_and_b32_e32 v181, 0xffff0000, v181
	v_pk_mul_f32 v[196:197], v[144:145], v[190:191] op_sel_hi:[1,0]
	s_nop 0
	v_pk_fma_f32 v[198:199], v[188:189], v[196:197], v[148:149] op_sel_hi:[0,1,1] neg_lo:[1,0,0] neg_hi:[1,0,0]
	v_pk_fma_f32 v[194:195], v[194:195], v[196:197], v[198:199]
	s_nop 0
	v_pk_fma_f32 v[124:125], v[194:195], s[12:13], v[124:125] op_sel_hi:[1,0,1]
	v_pk_mul_f32 v[194:195], v[146:147], v[190:191] op_sel_hi:[1,0]
	s_nop 0
	v_pk_fma_f32 v[196:197], v[188:189], v[194:195], v[150:151] op_sel_hi:[0,1,1] neg_lo:[1,0,0] neg_hi:[1,0,0]
	v_pk_fma_f32 v[180:181], v[180:181], v[194:195], v[196:197]
	v_pk_mul_f32 v[194:195], v[136:137], v[190:191] op_sel_hi:[1,0]
	v_pk_fma_f32 v[126:127], v[180:181], s[12:13], v[126:127] op_sel_hi:[1,0,1]
	v_lshlrev_b32_e32 v180, 16, v182
	v_and_b32_e32 v181, 0xffff0000, v182
	v_pk_fma_f32 v[196:197], v[188:189], v[194:195], v[140:141] op_sel_hi:[0,1,1] neg_lo:[1,0,0] neg_hi:[1,0,0]
	v_pk_fma_f32 v[180:181], v[180:181], v[194:195], v[196:197]
	s_nop 0
	v_pk_fma_f32 v[180:181], v[180:181], s[12:13], v[120:121] op_sel_hi:[1,0,1]
	v_lshlrev_b32_e32 v120, 16, v183
	v_and_b32_e32 v121, 0xffff0000, v183
	v_pk_mul_f32 v[182:183], v[138:139], v[190:191] op_sel_hi:[1,0]
	s_nop 0
	v_pk_fma_f32 v[188:189], v[188:189], v[182:183], v[142:143] op_sel_hi:[0,1,1] neg_lo:[1,0,0] neg_hi:[1,0,0]
	v_pk_fma_f32 v[120:121], v[120:121], v[182:183], v[188:189]
	s_nop 0
	v_pk_fma_f32 v[182:183], v[120:121], s[12:13], v[122:123] op_sel_hi:[1,0,1]
	v_cvt_pk_bf16_f32 v120, v124, v125
	v_cvt_pk_bf16_f32 v121, v126, v127
	v_cvt_pk_bf16_f32 v122, v180, v181
	v_cvt_pk_bf16_f32 v123, v182, v183
	v_lshlrev_b32_e32 v124, 16, v120
	global_store_dwordx4 v178, v[120:123], s[56:57]
	v_add_f32_e32 v180, 0, v124
	v_mul_f32_e32 v124, v124, v124
	v_and_b32_e32 v120, 0xffff0000, v120
	v_lshlrev_b32_e32 v125, 16, v121
	v_add_f32_e32 v180, v180, v120
	v_fmac_f32_e32 v124, v120, v120
	v_and_b32_e32 v121, 0xffff0000, v121
	v_add_f32_e32 v120, v180, v125
	v_fmac_f32_e32 v124, v125, v125
	v_lshlrev_b32_e32 v126, 16, v122
	v_add_f32_e32 v120, v120, v121
	v_fmac_f32_e32 v124, v121, v121
	v_and_b32_e32 v122, 0xffff0000, v122
	v_add_f32_e32 v120, v120, v126
	v_fmac_f32_e32 v124, v126, v126
	v_lshlrev_b32_e32 v127, 16, v123
	v_add_f32_e32 v120, v120, v122
	v_fmac_f32_e32 v124, v122, v122
	v_and_b32_e32 v123, 0xffff0000, v123
	v_add_f32_e32 v120, v120, v127
	v_fmac_f32_e32 v124, v127, v127
	v_add_f32_e32 v125, v120, v123
	v_fmac_f32_e32 v124, v123, v123
	ds_read2_b64 v[120:123], v177 offset1:16
	v_lshlrev_b32_e32 v180, 16, v184
	v_and_b32_e32 v181, 0xffff0000, v184
	s_waitcnt lgkmcnt(0)
	v_pk_mul_f32 v[122:123], v[122:123], s[96:97] op_sel_hi:[1,0]
	s_nop 0
	v_fma_f32 v126, -v122, v122, v123
	v_max_f32_e32 v126, 0, v126
	v_add_f32_e32 v126, 0x3727c5ac, v126
	v_rsq_f32_e32 v126, v126
	s_nop 0
	v_pk_mul_f32 v[182:183], v[144:145], v[126:127] op_sel_hi:[1,0]
	s_nop 0
	v_pk_fma_f32 v[188:189], v[122:123], v[182:183], v[148:149] op_sel_hi:[0,1,1] neg_lo:[1,0,0] neg_hi:[1,0,0]
	v_pk_fma_f32 v[180:181], v[180:181], v[182:183], v[188:189]
	v_pk_mul_f32 v[182:183], v[146:147], v[126:127] op_sel_hi:[1,0]
	v_pk_fma_f32 v[116:117], v[180:181], s[12:13], v[116:117] op_sel_hi:[1,0,1]
	v_lshlrev_b32_e32 v180, 16, v185
	v_and_b32_e32 v181, 0xffff0000, v185
	v_pk_fma_f32 v[184:185], v[122:123], v[182:183], v[150:151] op_sel_hi:[0,1,1] neg_lo:[1,0,0] neg_hi:[1,0,0]
	v_pk_fma_f32 v[180:181], v[180:181], v[182:183], v[184:185]
	v_pk_mul_f32 v[182:183], v[136:137], v[126:127] op_sel_hi:[1,0]
	v_pk_fma_f32 v[118:119], v[180:181], s[12:13], v[118:119] op_sel_hi:[1,0,1]
	v_lshlrev_b32_e32 v180, 16, v186
	v_and_b32_e32 v181, 0xffff0000, v186
	v_pk_fma_f32 v[184:185], v[122:123], v[182:183], v[140:141] op_sel_hi:[0,1,1] neg_lo:[1,0,0] neg_hi:[1,0,0]
	v_pk_fma_f32 v[180:181], v[180:181], v[182:183], v[184:185]
	v_pk_mul_f32 v[126:127], v[138:139], v[126:127] op_sel_hi:[1,0]
	v_pk_fma_f32 v[180:181], v[180:181], s[12:13], v[112:113] op_sel_hi:[1,0,1]
	v_lshlrev_b32_e32 v112, 16, v187
	v_and_b32_e32 v113, 0xffff0000, v187
	v_pk_fma_f32 v[122:123], v[122:123], v[126:127], v[142:143] op_sel_hi:[0,1,1] neg_lo:[1,0,0] neg_hi:[1,0,0]
	v_pk_fma_f32 v[112:113], v[112:113], v[126:127], v[122:123]
	s_nop 0
	v_pk_fma_f32 v[122:123], v[112:113], s[12:13], v[114:115] op_sel_hi:[1,0,1]
	v_cvt_pk_bf16_f32 v112, v116, v117
	v_cvt_pk_bf16_f32 v113, v118, v119
	v_cvt_pk_bf16_f32 v114, v180, v181
	v_cvt_pk_bf16_f32 v115, v122, v123
	v_lshlrev_b32_e32 v116, 16, v112
	global_store_dwordx4 v191, v[112:115], s[56:57]
	v_add_f32_e32 v122, 0, v116
	v_mul_f32_e32 v116, v116, v116
	v_and_b32_e32 v112, 0xffff0000, v112
	v_lshlrev_b32_e32 v117, 16, v113
	v_add_f32_e32 v122, v122, v112
	v_fmac_f32_e32 v116, v112, v112
	v_and_b32_e32 v113, 0xffff0000, v113
	v_add_f32_e32 v112, v122, v117
	v_fmac_f32_e32 v116, v117, v117
	v_lshlrev_b32_e32 v118, 16, v114
	v_add_f32_e32 v112, v112, v113
	v_fmac_f32_e32 v116, v113, v113
	v_and_b32_e32 v114, 0xffff0000, v114
	v_add_f32_e32 v112, v112, v118
	v_fmac_f32_e32 v116, v118, v118
	v_lshlrev_b32_e32 v119, 16, v115
	v_add_f32_e32 v112, v112, v114
	v_fmac_f32_e32 v116, v114, v114
	v_and_b32_e32 v115, 0xffff0000, v115
	v_add_f32_e32 v112, v112, v119
	v_fmac_f32_e32 v116, v119, v119
	v_add_f32_e32 v117, v112, v115
	v_fmac_f32_e32 v116, v115, v115
	ds_read2_b64 v[112:115], v177 offset0:16 offset1:32
	v_lshlrev_b32_e32 v122, 16, v166
	v_and_b32_e32 v123, 0xffff0000, v166
	s_waitcnt lgkmcnt(0)
	v_pk_mul_f32 v[114:115], v[114:115], s[96:97] op_sel_hi:[1,0]
	s_nop 0
	v_fma_f32 v118, -v114, v114, v115
	v_max_f32_e32 v118, 0, v118
	v_add_f32_e32 v118, 0x3727c5ac, v118
	v_rsq_f32_e32 v118, v118
	s_nop 0
	v_pk_mul_f32 v[126:127], v[144:145], v[118:119] op_sel_hi:[1,0]
	s_nop 0
	v_pk_fma_f32 v[180:181], v[114:115], v[126:127], v[148:149] op_sel_hi:[0,1,1] neg_lo:[1,0,0] neg_hi:[1,0,0]
	v_pk_fma_f32 v[122:123], v[122:123], v[126:127], v[180:181]
	v_pk_mul_f32 v[126:127], v[146:147], v[118:119] op_sel_hi:[1,0]
	v_pk_fma_f32 v[108:109], v[122:123], s[12:13], v[108:109] op_sel_hi:[1,0,1]
	v_lshlrev_b32_e32 v122, 16, v167
	v_and_b32_e32 v123, 0xffff0000, v167
	v_pk_fma_f32 v[166:167], v[114:115], v[126:127], v[150:151] op_sel_hi:[0,1,1] neg_lo:[1,0,0] neg_hi:[1,0,0]
	v_pk_fma_f32 v[122:123], v[122:123], v[126:127], v[166:167]
	v_pk_mul_f32 v[126:127], v[136:137], v[118:119] op_sel_hi:[1,0]
	v_pk_fma_f32 v[110:111], v[122:123], s[12:13], v[110:111] op_sel_hi:[1,0,1]
	v_lshlrev_b32_e32 v122, 16, v168
	v_and_b32_e32 v123, 0xffff0000, v168
	v_pk_fma_f32 v[166:167], v[114:115], v[126:127], v[140:141] op_sel_hi:[0,1,1] neg_lo:[1,0,0] neg_hi:[1,0,0]
	v_pk_fma_f32 v[122:123], v[122:123], v[126:127], v[166:167]
	v_pk_mul_f32 v[118:119], v[138:139], v[118:119] op_sel_hi:[1,0]
	v_pk_fma_f32 v[122:123], v[122:123], s[12:13], v[104:105] op_sel_hi:[1,0,1]
	v_lshlrev_b32_e32 v104, 16, v169
	v_and_b32_e32 v105, 0xffff0000, v169
	v_pk_fma_f32 v[114:115], v[114:115], v[118:119], v[142:143] op_sel_hi:[0,1,1] neg_lo:[1,0,0] neg_hi:[1,0,0]
	v_pk_fma_f32 v[104:105], v[104:105], v[118:119], v[114:115]
	s_nop 0
	v_pk_fma_f32 v[114:115], v[104:105], s[12:13], v[106:107] op_sel_hi:[1,0,1]
	v_cvt_pk_bf16_f32 v104, v108, v109
	v_cvt_pk_bf16_f32 v105, v110, v111
	v_cvt_pk_bf16_f32 v106, v122, v123
	v_cvt_pk_bf16_f32 v107, v114, v115
	v_lshlrev_b32_e32 v108, 16, v104
	global_store_dwordx4 v200, v[104:107], s[56:57]
	v_add_f32_e32 v115, 0, v108
	v_mul_f32_e32 v110, v108, v108
	v_and_b32_e32 v104, 0xffff0000, v104
	v_lshlrev_b32_e32 v109, 16, v105
	v_add_f32_e32 v108, v115, v104
	v_fmac_f32_e32 v110, v104, v104
	v_and_b32_e32 v105, 0xffff0000, v105
	v_add_f32_e32 v104, v108, v109
	v_fmac_f32_e32 v110, v109, v109
	v_lshlrev_b32_e32 v111, 16, v106
	v_add_f32_e32 v104, v104, v105
	v_fmac_f32_e32 v110, v105, v105
	v_and_b32_e32 v106, 0xffff0000, v106
	v_add_f32_e32 v104, v104, v111
	v_fmac_f32_e32 v110, v111, v111
	v_lshlrev_b32_e32 v114, 16, v107
	v_add_f32_e32 v104, v104, v106
	v_fmac_f32_e32 v110, v106, v106
	v_and_b32_e32 v107, 0xffff0000, v107
	v_add_f32_e32 v104, v104, v114
	v_fmac_f32_e32 v110, v114, v114
	v_add_f32_e32 v166, v104, v107
	v_fmac_f32_e32 v110, v107, v107
	ds_read2_b64 v[104:107], v177 offset0:32 offset1:48
	v_lshlrev_b32_e32 v114, 16, v162
	v_and_b32_e32 v115, 0xffff0000, v162
	s_waitcnt lgkmcnt(0)
	v_pk_mul_f32 v[106:107], v[106:107], s[96:97] op_sel_hi:[1,0]
	s_nop 0
	v_fma_f32 v108, -v106, v106, v107
	v_max_f32_e32 v108, 0, v108
	v_add_f32_e32 v108, 0x3727c5ac, v108
	v_rsq_f32_e32 v108, v108
	s_nop 0
	v_pk_mul_f32 v[118:119], v[144:145], v[108:109] op_sel_hi:[1,0]
	s_nop 0
	v_pk_fma_f32 v[122:123], v[106:107], v[118:119], v[148:149] op_sel_hi:[0,1,1] neg_lo:[1,0,0] neg_hi:[1,0,0]
	v_pk_fma_f32 v[114:115], v[114:115], v[118:119], v[122:123]
	v_pk_mul_f32 v[118:119], v[146:147], v[108:109] op_sel_hi:[1,0]
	v_pk_fma_f32 v[100:101], v[114:115], s[12:13], v[100:101] op_sel_hi:[1,0,1]
	v_lshlrev_b32_e32 v114, 16, v163
	v_and_b32_e32 v115, 0xffff0000, v163
	v_pk_fma_f32 v[122:123], v[106:107], v[118:119], v[150:151] op_sel_hi:[0,1,1] neg_lo:[1,0,0] neg_hi:[1,0,0]
	v_pk_fma_f32 v[114:115], v[114:115], v[118:119], v[122:123]
	v_pk_mul_f32 v[118:119], v[136:137], v[108:109] op_sel_hi:[1,0]
	v_pk_fma_f32 v[102:103], v[114:115], s[12:13], v[102:103] op_sel_hi:[1,0,1]
	v_lshlrev_b32_e32 v114, 16, v164
	v_and_b32_e32 v115, 0xffff0000, v164
	v_pk_fma_f32 v[122:123], v[106:107], v[118:119], v[140:141] op_sel_hi:[0,1,1] neg_lo:[1,0,0] neg_hi:[1,0,0]
	v_pk_fma_f32 v[114:115], v[114:115], v[118:119], v[122:123]
	v_pk_mul_f32 v[108:109], v[138:139], v[108:109] op_sel_hi:[1,0]
	v_pk_fma_f32 v[114:115], v[114:115], s[12:13], v[92:93] op_sel_hi:[1,0,1]
	v_lshlrev_b32_e32 v92, 16, v165
	v_and_b32_e32 v93, 0xffff0000, v165
	v_pk_fma_f32 v[106:107], v[106:107], v[108:109], v[142:143] op_sel_hi:[0,1,1] neg_lo:[1,0,0] neg_hi:[1,0,0]
	v_pk_fma_f32 v[92:93], v[92:93], v[108:109], v[106:107]
	v_pk_mul_f32 v[118:119], v[120:121], s[96:97] op_sel_hi:[1,0]
	v_pk_fma_f32 v[106:107], v[92:93], s[12:13], v[94:95] op_sel_hi:[1,0,1]
	v_cvt_pk_bf16_f32 v92, v100, v101
	v_cvt_pk_bf16_f32 v93, v102, v103
	v_cvt_pk_bf16_f32 v94, v114, v115
	v_cvt_pk_bf16_f32 v95, v106, v107
	v_lshlrev_b32_e32 v100, 16, v92
	global_store_dwordx4 v201, v[92:95], s[56:57]
	v_add_f32_e32 v106, 0, v100
	v_mul_f32_e32 v111, v100, v100
	v_and_b32_e32 v92, 0xffff0000, v92
	v_lshlrev_b32_e32 v101, 16, v93
	v_add_f32_e32 v100, v106, v92
	v_fmac_f32_e32 v111, v92, v92
	v_and_b32_e32 v93, 0xffff0000, v93
	v_add_f32_e32 v92, v100, v101
	v_fmac_f32_e32 v111, v101, v101
	v_lshlrev_b32_e32 v102, 16, v94
	v_add_f32_e32 v92, v92, v93
	v_fmac_f32_e32 v111, v93, v93
	v_and_b32_e32 v94, 0xffff0000, v94
	v_add_f32_e32 v92, v92, v102
	v_fmac_f32_e32 v111, v102, v102
	v_lshlrev_b32_e32 v103, 16, v95
	v_add_f32_e32 v92, v92, v94
	v_fmac_f32_e32 v111, v94, v94
	v_and_b32_e32 v95, 0xffff0000, v95
	v_add_f32_e32 v92, v92, v103
	v_fmac_f32_e32 v111, v103, v103
	v_add_f32_e32 v162, v92, v95
	v_fmac_f32_e32 v111, v95, v95
	ds_read2_b64 v[92:95], v177 offset0:48 offset1:128
	v_lshlrev_b32_e32 v102, 16, v156
	v_and_b32_e32 v103, 0xffff0000, v156
	v_add_u32_e32 v115, 0x58100, v178
	v_fma_f32 v120, -v118, v118, v119
	s_waitcnt lgkmcnt(0)
	v_pk_mul_f32 v[94:95], v[94:95], s[96:97] op_sel_hi:[1,0]
	v_max_f32_e32 v120, 0, v120
	v_fma_f32 v100, -v94, v94, v95
	v_max_f32_e32 v100, 0, v100
	v_add_f32_e32 v100, 0x3727c5ac, v100
	v_rsq_f32_e32 v100, v100
	v_add_f32_e32 v120, 0x3727c5ac, v120
	v_rsq_f32_e32 v120, v120
	v_pk_mul_f32 v[106:107], v[144:145], v[100:101] op_sel_hi:[1,0]
	s_nop 0
	v_pk_fma_f32 v[108:109], v[94:95], v[106:107], v[148:149] op_sel_hi:[0,1,1] neg_lo:[1,0,0] neg_hi:[1,0,0]
	v_pk_fma_f32 v[102:103], v[102:103], v[106:107], v[108:109]
	v_pk_mul_f32 v[106:107], v[146:147], v[100:101] op_sel_hi:[1,0]
	v_pk_fma_f32 v[96:97], v[102:103], s[12:13], v[96:97] op_sel_hi:[1,0,1]
	v_lshlrev_b32_e32 v102, 16, v157
	v_and_b32_e32 v103, 0xffff0000, v157
	v_pk_fma_f32 v[108:109], v[94:95], v[106:107], v[150:151] op_sel_hi:[0,1,1] neg_lo:[1,0,0] neg_hi:[1,0,0]
	v_pk_fma_f32 v[102:103], v[102:103], v[106:107], v[108:109]
	v_pk_mul_f32 v[106:107], v[136:137], v[100:101] op_sel_hi:[1,0]
	v_pk_fma_f32 v[98:99], v[102:103], s[12:13], v[98:99] op_sel_hi:[1,0,1]
	v_lshlrev_b32_e32 v102, 16, v158
	v_and_b32_e32 v103, 0xffff0000, v158
	v_pk_fma_f32 v[108:109], v[94:95], v[106:107], v[140:141] op_sel_hi:[0,1,1] neg_lo:[1,0,0] neg_hi:[1,0,0]
	v_pk_fma_f32 v[102:103], v[102:103], v[106:107], v[108:109]
	v_pk_mul_f32 v[100:101], v[138:139], v[100:101] op_sel_hi:[1,0]
	v_pk_fma_f32 v[102:103], v[102:103], s[12:13], v[88:89] op_sel_hi:[1,0,1]
	v_lshlrev_b32_e32 v88, 16, v159
	v_and_b32_e32 v89, 0xffff0000, v159
	v_pk_fma_f32 v[94:95], v[94:95], v[100:101], v[142:143] op_sel_hi:[0,1,1] neg_lo:[1,0,0] neg_hi:[1,0,0]
	v_pk_fma_f32 v[88:89], v[88:89], v[100:101], v[94:95]
	s_nop 0
	v_pk_fma_f32 v[94:95], v[88:89], s[12:13], v[90:91] op_sel_hi:[1,0,1]
	v_cvt_pk_bf16_f32 v88, v96, v97
	v_cvt_pk_bf16_f32 v89, v98, v99
	v_cvt_pk_bf16_f32 v90, v102, v103
	v_cvt_pk_bf16_f32 v91, v94, v95
	v_lshlrev_b32_e32 v94, 16, v88
	global_store_dwordx4 v202, v[88:91], s[56:57]
	v_add_f32_e32 v98, 0, v94
	v_mul_f32_e32 v114, v94, v94
	v_and_b32_e32 v88, 0xffff0000, v88
	v_lshlrev_b32_e32 v95, 16, v89
	v_add_f32_e32 v94, v98, v88
	v_fmac_f32_e32 v114, v88, v88
	v_and_b32_e32 v89, 0xffff0000, v89
	v_add_f32_e32 v88, v94, v95
	v_fmac_f32_e32 v114, v95, v95
	v_lshlrev_b32_e32 v96, 16, v90
	v_add_f32_e32 v88, v88, v89
	v_fmac_f32_e32 v114, v89, v89
	v_and_b32_e32 v90, 0xffff0000, v90
	v_add_f32_e32 v88, v88, v96
	v_fmac_f32_e32 v114, v96, v96
	v_lshlrev_b32_e32 v97, 16, v91
	v_add_f32_e32 v88, v88, v90
	v_fmac_f32_e32 v114, v90, v90
	v_and_b32_e32 v91, 0xffff0000, v91
	v_add_f32_e32 v88, v88, v97
	v_fmac_f32_e32 v114, v97, v97
	v_add_f32_e32 v156, v88, v91
	v_fmac_f32_e32 v114, v91, v91
	ds_read2_b64 v[88:91], v177 offset0:128 offset1:144
	v_lshlrev_b32_e32 v96, 16, v152
	v_and_b32_e32 v97, 0xffff0000, v152
	s_waitcnt lgkmcnt(0)
	v_pk_mul_f32 v[90:91], v[90:91], s[96:97] op_sel_hi:[1,0]
	s_nop 0
	v_fma_f32 v94, -v90, v90, v91
	v_max_f32_e32 v94, 0, v94
	v_add_f32_e32 v94, 0x3727c5ac, v94
	v_rsq_f32_e32 v94, v94
	s_nop 0
	v_pk_mul_f32 v[98:99], v[144:145], v[94:95] op_sel_hi:[1,0]
	s_nop 0
	v_pk_fma_f32 v[100:101], v[90:91], v[98:99], v[148:149] op_sel_hi:[0,1,1] neg_lo:[1,0,0] neg_hi:[1,0,0]
	v_pk_fma_f32 v[96:97], v[96:97], v[98:99], v[100:101]
	v_pk_mul_f32 v[98:99], v[146:147], v[94:95] op_sel_hi:[1,0]
	v_pk_fma_f32 v[84:85], v[96:97], s[12:13], v[84:85] op_sel_hi:[1,0,1]
	v_lshlrev_b32_e32 v96, 16, v153
	v_and_b32_e32 v97, 0xffff0000, v153
	v_pk_fma_f32 v[100:101], v[90:91], v[98:99], v[150:151] op_sel_hi:[0,1,1] neg_lo:[1,0,0] neg_hi:[1,0,0]
	v_pk_fma_f32 v[96:97], v[96:97], v[98:99], v[100:101]
	v_pk_mul_f32 v[98:99], v[136:137], v[94:95] op_sel_hi:[1,0]
	v_pk_fma_f32 v[86:87], v[96:97], s[12:13], v[86:87] op_sel_hi:[1,0,1]
	v_lshlrev_b32_e32 v96, 16, v154
	v_and_b32_e32 v97, 0xffff0000, v154
	v_pk_fma_f32 v[100:101], v[90:91], v[98:99], v[140:141] op_sel_hi:[0,1,1] neg_lo:[1,0,0] neg_hi:[1,0,0]
	v_pk_fma_f32 v[96:97], v[96:97], v[98:99], v[100:101]
	v_pk_mul_f32 v[94:95], v[138:139], v[94:95] op_sel_hi:[1,0]
	v_pk_fma_f32 v[96:97], v[96:97], s[12:13], v[24:25] op_sel_hi:[1,0,1]
	v_lshlrev_b32_e32 v24, 16, v155
	v_and_b32_e32 v25, 0xffff0000, v155
	v_pk_fma_f32 v[90:91], v[90:91], v[94:95], v[142:143] op_sel_hi:[0,1,1] neg_lo:[1,0,0] neg_hi:[1,0,0]
	v_pk_fma_f32 v[24:25], v[24:25], v[94:95], v[90:91]
	v_add_u32_e32 v154, 0x50100, v178
	v_pk_fma_f32 v[90:91], v[24:25], s[12:13], v[26:27] op_sel_hi:[1,0,1]
	v_cvt_pk_bf16_f32 v24, v84, v85
	v_cvt_pk_bf16_f32 v25, v86, v87
	v_cvt_pk_bf16_f32 v26, v96, v97
	v_cvt_pk_bf16_f32 v27, v90, v91
	v_lshlrev_b32_e32 v84, 16, v24
	global_store_dwordx4 v203, v[24:27], s[56:57]
	v_add_f32_e32 v91, 0, v84
	v_mul_f32_e32 v90, v84, v84
	v_and_b32_e32 v24, 0xffff0000, v24
	v_lshlrev_b32_e32 v85, 16, v25
	v_add_f32_e32 v84, v91, v24
	v_fmac_f32_e32 v90, v24, v24
	v_and_b32_e32 v25, 0xffff0000, v25
	v_add_f32_e32 v24, v84, v85
	v_fmac_f32_e32 v90, v85, v85
	v_lshlrev_b32_e32 v86, 16, v26
	v_add_f32_e32 v24, v24, v25
	v_fmac_f32_e32 v90, v25, v25
	v_and_b32_e32 v26, 0xffff0000, v26
	v_add_f32_e32 v24, v24, v86
	v_fmac_f32_e32 v90, v86, v86
	v_lshlrev_b32_e32 v87, 16, v27
	v_add_f32_e32 v24, v24, v26
	v_fmac_f32_e32 v90, v26, v26
	v_add_f32_e32 v24, v24, v87
	v_fmac_f32_e32 v90, v87, v87
	ds_read2_b64 v[84:87], v177 offset0:144 offset1:160
	v_and_b32_e32 v27, 0xffff0000, v27
	v_add_f32_e32 v152, v24, v27
	v_fmac_f32_e32 v90, v27, v27
	s_waitcnt lgkmcnt(0)
	v_pk_mul_f32 v[24:25], v[86:87], s[96:97] op_sel_hi:[1,0]
	s_nop 0
	v_fma_f32 v26, -v24, v24, v25
	v_max_f32_e32 v26, 0, v26
	v_add_f32_e32 v26, 0x3727c5ac, v26
	v_rsq_f32_e32 v26, v26
	v_lshlrev_b32_e32 v86, 16, v132
	v_and_b32_e32 v87, 0xffff0000, v132
	v_pk_mul_f32 v[94:95], v[144:145], v[26:27] op_sel_hi:[1,0]
	s_nop 0
	v_pk_fma_f32 v[96:97], v[24:25], v[94:95], v[148:149] op_sel_hi:[0,1,1] neg_lo:[1,0,0] neg_hi:[1,0,0]
	v_pk_fma_f32 v[86:87], v[86:87], v[94:95], v[96:97]
	v_pk_mul_f32 v[94:95], v[146:147], v[26:27] op_sel_hi:[1,0]
	v_pk_fma_f32 v[20:21], v[86:87], s[12:13], v[20:21] op_sel_hi:[1,0,1]
	v_lshlrev_b32_e32 v86, 16, v133
	v_and_b32_e32 v87, 0xffff0000, v133
	v_pk_fma_f32 v[96:97], v[24:25], v[94:95], v[150:151] op_sel_hi:[0,1,1] neg_lo:[1,0,0] neg_hi:[1,0,0]
	v_pk_fma_f32 v[86:87], v[86:87], v[94:95], v[96:97]
	v_pk_mul_f32 v[94:95], v[136:137], v[26:27] op_sel_hi:[1,0]
	v_pk_fma_f32 v[22:23], v[86:87], s[12:13], v[22:23] op_sel_hi:[1,0,1]
	v_lshlrev_b32_e32 v86, 16, v134
	v_and_b32_e32 v87, 0xffff0000, v134
	v_pk_fma_f32 v[96:97], v[24:25], v[94:95], v[140:141] op_sel_hi:[0,1,1] neg_lo:[1,0,0] neg_hi:[1,0,0]
	v_pk_fma_f32 v[86:87], v[86:87], v[94:95], v[96:97]
	v_pk_mul_f32 v[26:27], v[138:139], v[26:27] op_sel_hi:[1,0]
	v_pk_fma_f32 v[86:87], v[86:87], s[12:13], v[16:17] op_sel_hi:[1,0,1]
	v_lshlrev_b32_e32 v16, 16, v135
	v_and_b32_e32 v17, 0xffff0000, v135
	v_pk_fma_f32 v[24:25], v[24:25], v[26:27], v[142:143] op_sel_hi:[0,1,1] neg_lo:[1,0,0] neg_hi:[1,0,0]
	v_pk_fma_f32 v[16:17], v[16:17], v[26:27], v[24:25]
	ds_read2_b64 v[94:97], v177 offset0:160 offset1:176
	v_pk_fma_f32 v[24:25], v[16:17], s[12:13], v[18:19] op_sel_hi:[1,0,1]
	v_cvt_pk_bf16_f32 v16, v20, v21
	v_cvt_pk_bf16_f32 v17, v22, v23
	v_cvt_pk_bf16_f32 v18, v86, v87
	v_cvt_pk_bf16_f32 v19, v24, v25
	v_lshlrev_b32_e32 v20, 16, v16
	global_store_dwordx4 v204, v[16:19], s[56:57]
	v_add_f32_e32 v24, 0, v20
	v_lshlrev_b32_e32 v21, 16, v17
	v_and_b32_e32 v16, 0xffff0000, v16
	v_mul_f32_e32 v86, v20, v20
	v_add_f32_e32 v20, v24, v16
	v_and_b32_e32 v17, 0xffff0000, v17
	v_fmac_f32_e32 v86, v16, v16
	v_add_f32_e32 v16, v20, v21
	v_lshlrev_b32_e32 v22, 16, v18
	v_add_f32_e32 v16, v16, v17
	v_and_b32_e32 v18, 0xffff0000, v18
	v_add_f32_e32 v16, v16, v22
	v_lshlrev_b32_e32 v23, 16, v19
	v_fmac_f32_e32 v86, v21, v21
	v_add_f32_e32 v16, v16, v18
	v_and_b32_e32 v19, 0xffff0000, v19
	v_fmac_f32_e32 v86, v17, v17
	v_add_f32_e32 v16, v16, v23
	v_fmac_f32_e32 v86, v22, v22
	v_add_f32_e32 v153, v16, v19
	s_waitcnt lgkmcnt(0)
	v_pk_mul_f32 v[16:17], v[96:97], s[96:97] op_sel_hi:[1,0]
	v_fmac_f32_e32 v86, v18, v18
	v_fma_f32 v18, -v16, v16, v17
	v_max_f32_e32 v18, 0, v18
	v_add_f32_e32 v18, 0x3727c5ac, v18
	v_rsq_f32_e32 v18, v18
	v_fmac_f32_e32 v86, v23, v23
	v_lshlrev_b32_e32 v20, 16, v128
	v_and_b32_e32 v21, 0xffff0000, v128
	v_pk_mul_f32 v[22:23], v[144:145], v[18:19] op_sel_hi:[1,0]
	v_fmac_f32_e32 v86, v19, v19
	v_pk_fma_f32 v[24:25], v[16:17], v[22:23], v[148:149] op_sel_hi:[0,1,1] neg_lo:[1,0,0] neg_hi:[1,0,0]
	v_pk_fma_f32 v[20:21], v[20:21], v[22:23], v[24:25]
	v_pk_mul_f32 v[22:23], v[146:147], v[18:19] op_sel_hi:[1,0]
	v_pk_fma_f32 v[12:13], v[20:21], s[12:13], v[12:13] op_sel_hi:[1,0,1]
	v_lshlrev_b32_e32 v20, 16, v129
	v_and_b32_e32 v21, 0xffff0000, v129
	v_pk_fma_f32 v[24:25], v[16:17], v[22:23], v[150:151] op_sel_hi:[0,1,1] neg_lo:[1,0,0] neg_hi:[1,0,0]
	v_pk_fma_f32 v[20:21], v[20:21], v[22:23], v[24:25]
	v_pk_mul_f32 v[22:23], v[136:137], v[18:19] op_sel_hi:[1,0]
	v_pk_fma_f32 v[14:15], v[20:21], s[12:13], v[14:15] op_sel_hi:[1,0,1]
	v_lshlrev_b32_e32 v20, 16, v130
	v_and_b32_e32 v21, 0xffff0000, v130
	v_pk_fma_f32 v[24:25], v[16:17], v[22:23], v[140:141] op_sel_hi:[0,1,1] neg_lo:[1,0,0] neg_hi:[1,0,0]
	v_pk_fma_f32 v[20:21], v[20:21], v[22:23], v[24:25]
	v_pk_mul_f32 v[18:19], v[138:139], v[18:19] op_sel_hi:[1,0]
	v_pk_fma_f32 v[20:21], v[20:21], s[12:13], v[8:9] op_sel_hi:[1,0,1]
	v_lshlrev_b32_e32 v8, 16, v131
	v_and_b32_e32 v9, 0xffff0000, v131
	v_pk_fma_f32 v[16:17], v[16:17], v[18:19], v[142:143] op_sel_hi:[0,1,1] neg_lo:[1,0,0] neg_hi:[1,0,0]
	v_pk_fma_f32 v[8:9], v[8:9], v[18:19], v[16:17]
	v_add_u32_e32 v146, 0x100, v178
	v_pk_fma_f32 v[16:17], v[8:9], s[12:13], v[10:11] op_sel_hi:[1,0,1]
	v_cvt_pk_bf16_f32 v8, v12, v13
	v_cvt_pk_bf16_f32 v9, v14, v15
	v_cvt_pk_bf16_f32 v10, v20, v21
	v_cvt_pk_bf16_f32 v11, v16, v17
	v_lshlrev_b32_e32 v12, 16, v8
	global_store_dwordx4 v179, v[8:11], s[56:57]
	v_add_f32_e32 v16, 0, v12
	v_mul_f32_e32 v87, v12, v12
	v_and_b32_e32 v8, 0xffff0000, v8
	v_lshlrev_b32_e32 v13, 16, v9
	v_add_f32_e32 v12, v16, v8
	v_fmac_f32_e32 v87, v8, v8
	v_and_b32_e32 v9, 0xffff0000, v9
	v_add_f32_e32 v8, v12, v13
	v_fmac_f32_e32 v87, v13, v13
	v_lshlrev_b32_e32 v14, 16, v10
	v_add_f32_e32 v8, v8, v9
	v_fmac_f32_e32 v87, v9, v9
	v_and_b32_e32 v10, 0xffff0000, v10
	v_add_f32_e32 v8, v8, v14
	v_fmac_f32_e32 v87, v14, v14
	v_lshlrev_b32_e32 v15, 16, v11
	v_add_f32_e32 v8, v8, v10
	v_fmac_f32_e32 v87, v10, v10
	v_and_b32_e32 v11, 0xffff0000, v11
	v_add_f32_e32 v8, v8, v15
	v_fmac_f32_e32 v87, v15, v15
	v_add_u32_e32 v147, 0x8100, v178
	v_add_u32_e32 v148, 0x10100, v178
	v_add_u32_e32 v149, 0x18100, v178
	v_add_u32_e32 v150, 0x40100, v178
	v_add_u32_e32 v151, 0x48100, v178
	v_add_f32_e32 v91, v8, v11
	v_fmac_f32_e32 v87, v11, v11
	global_load_dwordx4 v[126:129], v146, s[50:51] nt
	global_load_dwordx4 v[130:133], v147, s[50:51] nt
	global_load_dwordx4 v[134:137], v148, s[50:51] nt
	global_load_dwordx4 v[138:141], v149, s[50:51] nt
	global_load_dwordx4 v[106:109], v150, s[50:51] nt
	global_load_dwordx4 v[100:103], v151, s[50:51] nt
	global_load_dwordx4 v[96:99], v154, s[50:51] nt
	global_load_dwordx4 v[16:19], v115, s[50:51] nt
	global_load_dwordx4 v[8:11], v[170:171], off offset:528
	global_load_dwordx4 v[20:23], v[170:171], off offset:512
	global_load_dwordx4 v[12:15], v[172:173], off offset:528
	global_load_dwordx4 v[24:27], v[172:173], off offset:512
	s_waitcnt vmcnt(11)
	v_lshlrev_b32_e32 v122, 16, v126
	v_and_b32_e32 v123, 0xffff0000, v126
	s_waitcnt vmcnt(2)
	v_pk_mul_f32 v[142:143], v[20:21], v[120:121] op_sel_hi:[1,0]
	s_waitcnt vmcnt(0)
	v_pk_fma_f32 v[144:145], v[118:119], v[142:143], v[24:25] op_sel_hi:[0,1,1] neg_lo:[1,0,0] neg_hi:[1,0,0]
	v_pk_fma_f32 v[122:123], v[122:123], v[142:143], v[144:145]
	s_nop 0
	v_pk_fma_f32 v[80:81], v[122:123], s[12:13], v[80:81] op_sel_hi:[1,0,1]
	v_lshlrev_b32_e32 v122, 16, v127
	v_and_b32_e32 v123, 0xffff0000, v127
	v_pk_mul_f32 v[126:127], v[22:23], v[120:121] op_sel_hi:[1,0]
	s_nop 0
	v_pk_fma_f32 v[142:143], v[118:119], v[126:127], v[26:27] op_sel_hi:[0,1,1] neg_lo:[1,0,0] neg_hi:[1,0,0]
	v_pk_fma_f32 v[122:123], v[122:123], v[126:127], v[142:143]
	v_pk_mul_f32 v[126:127], v[8:9], v[120:121] op_sel_hi:[1,0]
	v_pk_fma_f32 v[82:83], v[122:123], s[12:13], v[82:83] op_sel_hi:[1,0,1]
	v_lshlrev_b32_e32 v122, 16, v128
	v_and_b32_e32 v123, 0xffff0000, v128
	v_pk_fma_f32 v[142:143], v[118:119], v[126:127], v[12:13] op_sel_hi:[0,1,1] neg_lo:[1,0,0] neg_hi:[1,0,0]
	v_pk_fma_f32 v[122:123], v[122:123], v[126:127], v[142:143]
	v_pk_mul_f32 v[120:121], v[10:11], v[120:121] op_sel_hi:[1,0]
	v_pk_fma_f32 v[122:123], v[122:123], s[12:13], v[76:77] op_sel_hi:[1,0,1]
	v_lshlrev_b32_e32 v76, 16, v129
	v_and_b32_e32 v77, 0xffff0000, v129
	v_pk_fma_f32 v[118:119], v[118:119], v[120:121], v[14:15] op_sel_hi:[0,1,1] neg_lo:[1,0,0] neg_hi:[1,0,0]
	v_pk_fma_f32 v[76:77], v[76:77], v[120:121], v[118:119]
	s_nop 0
	v_pk_fma_f32 v[118:119], v[76:77], s[12:13], v[78:79] op_sel_hi:[1,0,1]
	v_cvt_pk_bf16_f32 v76, v80, v81
	v_cvt_pk_bf16_f32 v77, v82, v83
	v_cvt_pk_bf16_f32 v78, v122, v123
	v_cvt_pk_bf16_f32 v79, v118, v119
	v_lshlrev_b32_e32 v80, 16, v76
	global_store_dwordx4 v146, v[76:79], s[56:57]
	v_add_f32_e32 v118, v125, v80
	v_fmac_f32_e32 v124, v80, v80
	v_and_b32_e32 v76, 0xffff0000, v76
	v_lshlrev_b32_e32 v81, 16, v77
	v_add_f32_e32 v80, v118, v76
	v_fmac_f32_e32 v124, v76, v76
	v_and_b32_e32 v77, 0xffff0000, v77
	v_add_f32_e32 v76, v80, v81
	v_fmac_f32_e32 v124, v81, v81
	v_lshlrev_b32_e32 v82, 16, v78
	v_add_f32_e32 v76, v76, v77
	v_fmac_f32_e32 v124, v77, v77
	v_and_b32_e32 v78, 0xffff0000, v78
	v_add_f32_e32 v76, v76, v82
	v_fmac_f32_e32 v124, v82, v82
	v_lshlrev_b32_e32 v83, 16, v79
	v_add_f32_e32 v76, v76, v78
	v_fmac_f32_e32 v124, v78, v78
	v_and_b32_e32 v79, 0xffff0000, v79
	v_add_f32_e32 v76, v76, v83
	v_fmac_f32_e32 v124, v83, v83
	v_add_f32_e32 v76, v76, v79
	v_fmac_f32_e32 v124, v79, v79
	v_pk_mul_f32 v[78:79], v[112:113], s[96:97] op_sel_hi:[1,0]
	v_lshlrev_b32_e32 v82, 16, v130
	v_fma_f32 v77, -v78, v78, v79
	v_max_f32_e32 v77, 0, v77
	v_add_f32_e32 v77, 0x3727c5ac, v77
	v_rsq_f32_e32 v80, v77
	v_and_b32_e32 v83, 0xffff0000, v130
	v_pk_mul_f32 v[112:113], v[20:21], v[80:81] op_sel_hi:[1,0]
	s_nop 0
	v_pk_fma_f32 v[118:119], v[78:79], v[112:113], v[24:25] op_sel_hi:[0,1,1] neg_lo:[1,0,0] neg_hi:[1,0,0]
	v_pk_fma_f32 v[82:83], v[82:83], v[112:113], v[118:119]
	v_pk_mul_f32 v[112:113], v[22:23], v[80:81] op_sel_hi:[1,0]
	v_pk_fma_f32 v[72:73], v[82:83], s[12:13], v[72:73] op_sel_hi:[1,0,1]
	v_lshlrev_b32_e32 v82, 16, v131
	v_and_b32_e32 v83, 0xffff0000, v131
	v_pk_fma_f32 v[118:119], v[78:79], v[112:113], v[26:27] op_sel_hi:[0,1,1] neg_lo:[1,0,0] neg_hi:[1,0,0]
	v_pk_fma_f32 v[82:83], v[82:83], v[112:113], v[118:119]
	v_pk_mul_f32 v[112:113], v[8:9], v[80:81] op_sel_hi:[1,0]
	v_pk_fma_f32 v[74:75], v[82:83], s[12:13], v[74:75] op_sel_hi:[1,0,1]
	v_lshlrev_b32_e32 v82, 16, v132
	v_and_b32_e32 v83, 0xffff0000, v132
	v_pk_fma_f32 v[118:119], v[78:79], v[112:113], v[12:13] op_sel_hi:[0,1,1] neg_lo:[1,0,0] neg_hi:[1,0,0]
	v_pk_fma_f32 v[82:83], v[82:83], v[112:113], v[118:119]
	v_pk_mul_f32 v[80:81], v[10:11], v[80:81] op_sel_hi:[1,0]
	v_pk_fma_f32 v[82:83], v[82:83], s[12:13], v[68:69] op_sel_hi:[1,0,1]
	v_lshlrev_b32_e32 v68, 16, v133
	v_and_b32_e32 v69, 0xffff0000, v133
	v_pk_fma_f32 v[78:79], v[78:79], v[80:81], v[14:15] op_sel_hi:[0,1,1] neg_lo:[1,0,0] neg_hi:[1,0,0]
	v_pk_fma_f32 v[68:69], v[68:69], v[80:81], v[78:79]
	s_nop 0
	v_pk_fma_f32 v[78:79], v[68:69], s[12:13], v[70:71] op_sel_hi:[1,0,1]
	v_cvt_pk_bf16_f32 v68, v72, v73
	v_cvt_pk_bf16_f32 v69, v74, v75
	v_cvt_pk_bf16_f32 v70, v82, v83
	v_cvt_pk_bf16_f32 v71, v78, v79
	v_lshlrev_b32_e32 v72, 16, v68
	global_store_dwordx4 v147, v[68:71], s[56:57]
	v_add_f32_e32 v77, v117, v72
	v_fmac_f32_e32 v116, v72, v72
	v_and_b32_e32 v68, 0xffff0000, v68
	v_lshlrev_b32_e32 v73, 16, v69
	v_add_f32_e32 v72, v77, v68
	v_fmac_f32_e32 v116, v68, v68
	v_and_b32_e32 v69, 0xffff0000, v69
	v_add_f32_e32 v68, v72, v73
	v_fmac_f32_e32 v116, v73, v73
	v_lshlrev_b32_e32 v74, 16, v70
	v_add_f32_e32 v68, v68, v69
	v_fmac_f32_e32 v116, v69, v69
	v_and_b32_e32 v70, 0xffff0000, v70
	v_add_f32_e32 v68, v68, v74
	v_fmac_f32_e32 v116, v74, v74
	v_lshlrev_b32_e32 v75, 16, v71
	v_add_f32_e32 v68, v68, v70
	v_fmac_f32_e32 v116, v70, v70
	v_and_b32_e32 v71, 0xffff0000, v71
	v_add_f32_e32 v68, v68, v75
	v_fmac_f32_e32 v116, v75, v75
	v_add_f32_e32 v68, v68, v71
	v_fmac_f32_e32 v116, v71, v71
	v_pk_mul_f32 v[70:71], v[104:105], s[96:97] op_sel_hi:[1,0]
	v_lshlrev_b32_e32 v74, 16, v134
	v_fma_f32 v69, -v70, v70, v71
	v_max_f32_e32 v69, 0, v69
	v_add_f32_e32 v69, 0x3727c5ac, v69
	v_rsq_f32_e32 v72, v69
	v_and_b32_e32 v75, 0xffff0000, v134
	v_pk_mul_f32 v[78:79], v[20:21], v[72:73] op_sel_hi:[1,0]
	s_nop 0
	v_pk_fma_f32 v[80:81], v[70:71], v[78:79], v[24:25] op_sel_hi:[0,1,1] neg_lo:[1,0,0] neg_hi:[1,0,0]
	v_pk_fma_f32 v[74:75], v[74:75], v[78:79], v[80:81]
	v_pk_mul_f32 v[78:79], v[22:23], v[72:73] op_sel_hi:[1,0]
	v_pk_fma_f32 v[64:65], v[74:75], s[12:13], v[64:65] op_sel_hi:[1,0,1]
	v_lshlrev_b32_e32 v74, 16, v135
	v_and_b32_e32 v75, 0xffff0000, v135
	v_pk_fma_f32 v[80:81], v[70:71], v[78:79], v[26:27] op_sel_hi:[0,1,1] neg_lo:[1,0,0] neg_hi:[1,0,0]
	v_pk_fma_f32 v[74:75], v[74:75], v[78:79], v[80:81]
	v_pk_mul_f32 v[78:79], v[8:9], v[72:73] op_sel_hi:[1,0]
	v_pk_fma_f32 v[66:67], v[74:75], s[12:13], v[66:67] op_sel_hi:[1,0,1]
	v_lshlrev_b32_e32 v74, 16, v136
	v_and_b32_e32 v75, 0xffff0000, v136
	v_pk_fma_f32 v[80:81], v[70:71], v[78:79], v[12:13] op_sel_hi:[0,1,1] neg_lo:[1,0,0] neg_hi:[1,0,0]
	v_pk_fma_f32 v[74:75], v[74:75], v[78:79], v[80:81]
	v_pk_mul_f32 v[72:73], v[10:11], v[72:73] op_sel_hi:[1,0]
	v_pk_fma_f32 v[74:75], v[74:75], s[12:13], v[60:61] op_sel_hi:[1,0,1]
	v_lshlrev_b32_e32 v60, 16, v137
	v_and_b32_e32 v61, 0xffff0000, v137
	v_pk_fma_f32 v[70:71], v[70:71], v[72:73], v[14:15] op_sel_hi:[0,1,1] neg_lo:[1,0,0] neg_hi:[1,0,0]
	v_pk_fma_f32 v[60:61], v[60:61], v[72:73], v[70:71]
	s_nop 0
	v_pk_fma_f32 v[70:71], v[60:61], s[12:13], v[62:63] op_sel_hi:[1,0,1]
	v_cvt_pk_bf16_f32 v60, v64, v65
	v_cvt_pk_bf16_f32 v61, v66, v67
	v_cvt_pk_bf16_f32 v62, v74, v75
	v_cvt_pk_bf16_f32 v63, v70, v71
	v_lshlrev_b32_e32 v64, 16, v60
	global_store_dwordx4 v148, v[60:63], s[56:57]
	v_add_f32_e32 v69, v166, v64
	v_fmac_f32_e32 v110, v64, v64
	v_and_b32_e32 v60, 0xffff0000, v60
	v_lshlrev_b32_e32 v65, 16, v61
	v_add_f32_e32 v64, v69, v60
	v_fmac_f32_e32 v110, v60, v60
	v_and_b32_e32 v61, 0xffff0000, v61
	v_add_f32_e32 v60, v64, v65
	v_fmac_f32_e32 v110, v65, v65
	v_lshlrev_b32_e32 v66, 16, v62
	v_add_f32_e32 v60, v60, v61
	v_fmac_f32_e32 v110, v61, v61
	v_and_b32_e32 v62, 0xffff0000, v62
	v_add_f32_e32 v60, v60, v66
	v_fmac_f32_e32 v110, v66, v66
	v_lshlrev_b32_e32 v67, 16, v63
	v_add_f32_e32 v60, v60, v62
	v_fmac_f32_e32 v110, v62, v62
	v_and_b32_e32 v63, 0xffff0000, v63
	v_add_f32_e32 v60, v60, v67
	v_fmac_f32_e32 v110, v67, v67
	v_add_f32_e32 v60, v60, v63
	v_fmac_f32_e32 v110, v63, v63
	v_pk_mul_f32 v[62:63], v[92:93], s[96:97] op_sel_hi:[1,0]
	v_lshlrev_b32_e32 v66, 16, v138
	v_fma_f32 v61, -v62, v62, v63
	v_max_f32_e32 v61, 0, v61
	v_add_f32_e32 v61, 0x3727c5ac, v61
	v_rsq_f32_e32 v64, v61
	v_and_b32_e32 v67, 0xffff0000, v138
	v_pk_mul_f32 v[70:71], v[20:21], v[64:65] op_sel_hi:[1,0]
	s_nop 0
	v_pk_fma_f32 v[72:73], v[62:63], v[70:71], v[24:25] op_sel_hi:[0,1,1] neg_lo:[1,0,0] neg_hi:[1,0,0]
	v_pk_fma_f32 v[66:67], v[66:67], v[70:71], v[72:73]
	v_pk_mul_f32 v[70:71], v[22:23], v[64:65] op_sel_hi:[1,0]
	v_pk_fma_f32 v[56:57], v[66:67], s[12:13], v[56:57] op_sel_hi:[1,0,1]
	v_lshlrev_b32_e32 v66, 16, v139
	v_and_b32_e32 v67, 0xffff0000, v139
	v_pk_fma_f32 v[72:73], v[62:63], v[70:71], v[26:27] op_sel_hi:[0,1,1] neg_lo:[1,0,0] neg_hi:[1,0,0]
	v_pk_fma_f32 v[66:67], v[66:67], v[70:71], v[72:73]
	v_pk_mul_f32 v[70:71], v[8:9], v[64:65] op_sel_hi:[1,0]
	v_pk_fma_f32 v[58:59], v[66:67], s[12:13], v[58:59] op_sel_hi:[1,0,1]
	v_lshlrev_b32_e32 v66, 16, v140
	v_and_b32_e32 v67, 0xffff0000, v140
	v_pk_fma_f32 v[72:73], v[62:63], v[70:71], v[12:13] op_sel_hi:[0,1,1] neg_lo:[1,0,0] neg_hi:[1,0,0]
	v_pk_fma_f32 v[66:67], v[66:67], v[70:71], v[72:73]
	v_pk_mul_f32 v[64:65], v[10:11], v[64:65] op_sel_hi:[1,0]
	v_pk_fma_f32 v[66:67], v[66:67], s[12:13], v[48:49] op_sel_hi:[1,0,1]
	v_lshlrev_b32_e32 v48, 16, v141
	v_and_b32_e32 v49, 0xffff0000, v141
	v_pk_fma_f32 v[62:63], v[62:63], v[64:65], v[14:15] op_sel_hi:[0,1,1] neg_lo:[1,0,0] neg_hi:[1,0,0]
	v_pk_fma_f32 v[48:49], v[48:49], v[64:65], v[62:63]
	s_nop 0
	v_pk_fma_f32 v[62:63], v[48:49], s[12:13], v[50:51] op_sel_hi:[1,0,1]
	v_cvt_pk_bf16_f32 v48, v56, v57
	v_cvt_pk_bf16_f32 v49, v58, v59
	v_cvt_pk_bf16_f32 v50, v66, v67
	v_cvt_pk_bf16_f32 v51, v62, v63
	v_lshlrev_b32_e32 v56, 16, v48
	global_store_dwordx4 v149, v[48:51], s[56:57]
	v_add_f32_e32 v61, v162, v56
	v_fmac_f32_e32 v111, v56, v56
	v_and_b32_e32 v48, 0xffff0000, v48
	v_lshlrev_b32_e32 v57, 16, v49
	v_add_f32_e32 v56, v61, v48
	v_fmac_f32_e32 v111, v48, v48
	v_and_b32_e32 v49, 0xffff0000, v49
	v_add_f32_e32 v48, v56, v57
	v_fmac_f32_e32 v111, v57, v57
	v_lshlrev_b32_e32 v58, 16, v50
	v_add_f32_e32 v48, v48, v49
	v_fmac_f32_e32 v111, v49, v49
	v_and_b32_e32 v50, 0xffff0000, v50
	v_add_f32_e32 v48, v48, v58
	v_fmac_f32_e32 v111, v58, v58
	v_lshlrev_b32_e32 v59, 16, v51
	v_add_f32_e32 v48, v48, v50
	v_fmac_f32_e32 v111, v50, v50
	v_and_b32_e32 v51, 0xffff0000, v51
	v_add_f32_e32 v48, v48, v59
	v_fmac_f32_e32 v111, v59, v59
	v_add_f32_e32 v48, v48, v51
	v_fmac_f32_e32 v111, v51, v51
	v_pk_mul_f32 v[50:51], v[88:89], s[96:97] op_sel_hi:[1,0]
	v_lshlrev_b32_e32 v58, 16, v106
	v_fma_f32 v49, -v50, v50, v51
	v_max_f32_e32 v49, 0, v49
	v_add_f32_e32 v49, 0x3727c5ac, v49
	v_rsq_f32_e32 v56, v49
	v_and_b32_e32 v59, 0xffff0000, v106
	v_pk_mul_f32 v[62:63], v[20:21], v[56:57] op_sel_hi:[1,0]
	s_nop 0
	v_pk_fma_f32 v[64:65], v[50:51], v[62:63], v[24:25] op_sel_hi:[0,1,1] neg_lo:[1,0,0] neg_hi:[1,0,0]
	v_pk_fma_f32 v[58:59], v[58:59], v[62:63], v[64:65]
	v_pk_mul_f32 v[62:63], v[22:23], v[56:57] op_sel_hi:[1,0]
	v_pk_fma_f32 v[52:53], v[58:59], s[12:13], v[52:53] op_sel_hi:[1,0,1]
	v_lshlrev_b32_e32 v58, 16, v107
	v_and_b32_e32 v59, 0xffff0000, v107
	v_pk_fma_f32 v[64:65], v[50:51], v[62:63], v[26:27] op_sel_hi:[0,1,1] neg_lo:[1,0,0] neg_hi:[1,0,0]
	v_pk_fma_f32 v[58:59], v[58:59], v[62:63], v[64:65]
	v_pk_mul_f32 v[62:63], v[8:9], v[56:57] op_sel_hi:[1,0]
	v_pk_fma_f32 v[54:55], v[58:59], s[12:13], v[54:55] op_sel_hi:[1,0,1]
	v_lshlrev_b32_e32 v58, 16, v108
	v_and_b32_e32 v59, 0xffff0000, v108
	v_pk_fma_f32 v[64:65], v[50:51], v[62:63], v[12:13] op_sel_hi:[0,1,1] neg_lo:[1,0,0] neg_hi:[1,0,0]
	v_pk_fma_f32 v[58:59], v[58:59], v[62:63], v[64:65]
	v_pk_mul_f32 v[56:57], v[10:11], v[56:57] op_sel_hi:[1,0]
	v_pk_fma_f32 v[58:59], v[58:59], s[12:13], v[44:45] op_sel_hi:[1,0,1]
	v_lshlrev_b32_e32 v44, 16, v109
	v_and_b32_e32 v45, 0xffff0000, v109
	v_pk_fma_f32 v[50:51], v[50:51], v[56:57], v[14:15] op_sel_hi:[0,1,1] neg_lo:[1,0,0] neg_hi:[1,0,0]
	v_pk_fma_f32 v[44:45], v[44:45], v[56:57], v[50:51]
	s_nop 0
	v_pk_fma_f32 v[50:51], v[44:45], s[12:13], v[46:47] op_sel_hi:[1,0,1]
	v_cvt_pk_bf16_f32 v44, v52, v53
	v_cvt_pk_bf16_f32 v45, v54, v55
	v_cvt_pk_bf16_f32 v46, v58, v59
	v_cvt_pk_bf16_f32 v47, v50, v51
	v_lshlrev_b32_e32 v49, 16, v44
	global_store_dwordx4 v150, v[44:47], s[56:57]
	v_add_f32_e32 v53, v156, v49
	v_fmac_f32_e32 v114, v49, v49
	v_and_b32_e32 v44, 0xffff0000, v44
	v_lshlrev_b32_e32 v50, 16, v45
	v_add_f32_e32 v49, v53, v44
	v_fmac_f32_e32 v114, v44, v44
	v_and_b32_e32 v45, 0xffff0000, v45
	v_add_f32_e32 v44, v49, v50
	v_fmac_f32_e32 v114, v50, v50
	v_lshlrev_b32_e32 v51, 16, v46
	v_add_f32_e32 v44, v44, v45
	v_fmac_f32_e32 v114, v45, v45
	v_and_b32_e32 v46, 0xffff0000, v46
	v_add_f32_e32 v44, v44, v51
	v_fmac_f32_e32 v114, v51, v51
	v_lshlrev_b32_e32 v52, 16, v47
	v_add_f32_e32 v44, v44, v46
	v_fmac_f32_e32 v114, v46, v46
	v_and_b32_e32 v47, 0xffff0000, v47
	v_add_f32_e32 v44, v44, v52
	v_fmac_f32_e32 v114, v52, v52
	v_add_f32_e32 v44, v44, v47
	v_fmac_f32_e32 v114, v47, v47
	v_pk_mul_f32 v[46:47], v[84:85], s[96:97] op_sel_hi:[1,0]
	v_lshlrev_b32_e32 v52, 16, v100
	v_fma_f32 v45, -v46, v46, v47
	v_max_f32_e32 v45, 0, v45
	v_add_f32_e32 v45, 0x3727c5ac, v45
	v_rsq_f32_e32 v50, v45
	v_and_b32_e32 v53, 0xffff0000, v100
	v_pk_mul_f32 v[54:55], v[20:21], v[50:51] op_sel_hi:[1,0]
	s_nop 0
	v_pk_fma_f32 v[56:57], v[46:47], v[54:55], v[24:25] op_sel_hi:[0,1,1] neg_lo:[1,0,0] neg_hi:[1,0,0]
	v_pk_fma_f32 v[52:53], v[52:53], v[54:55], v[56:57]
	v_pk_mul_f32 v[54:55], v[22:23], v[50:51] op_sel_hi:[1,0]
	v_pk_fma_f32 v[40:41], v[52:53], s[12:13], v[40:41] op_sel_hi:[1,0,1]
	v_lshlrev_b32_e32 v52, 16, v101
	v_and_b32_e32 v53, 0xffff0000, v101
	v_pk_fma_f32 v[56:57], v[46:47], v[54:55], v[26:27] op_sel_hi:[0,1,1] neg_lo:[1,0,0] neg_hi:[1,0,0]
	v_pk_fma_f32 v[52:53], v[52:53], v[54:55], v[56:57]
	v_pk_mul_f32 v[54:55], v[8:9], v[50:51] op_sel_hi:[1,0]
	v_pk_fma_f32 v[42:43], v[52:53], s[12:13], v[42:43] op_sel_hi:[1,0,1]
	v_lshlrev_b32_e32 v52, 16, v102
	v_and_b32_e32 v53, 0xffff0000, v102
	v_pk_fma_f32 v[56:57], v[46:47], v[54:55], v[12:13] op_sel_hi:[0,1,1] neg_lo:[1,0,0] neg_hi:[1,0,0]
	v_pk_fma_f32 v[52:53], v[52:53], v[54:55], v[56:57]
	v_pk_mul_f32 v[50:51], v[10:11], v[50:51] op_sel_hi:[1,0]
	v_pk_fma_f32 v[52:53], v[52:53], s[12:13], v[36:37] op_sel_hi:[1,0,1]
	v_lshlrev_b32_e32 v36, 16, v103
	v_and_b32_e32 v37, 0xffff0000, v103
	v_pk_fma_f32 v[46:47], v[46:47], v[50:51], v[14:15] op_sel_hi:[0,1,1] neg_lo:[1,0,0] neg_hi:[1,0,0]
	v_pk_fma_f32 v[36:37], v[36:37], v[50:51], v[46:47]
	s_nop 0
	v_pk_fma_f32 v[46:47], v[36:37], s[12:13], v[38:39] op_sel_hi:[1,0,1]
	v_cvt_pk_bf16_f32 v36, v40, v41
	v_cvt_pk_bf16_f32 v37, v42, v43
	v_cvt_pk_bf16_f32 v38, v52, v53
	v_cvt_pk_bf16_f32 v39, v46, v47
	v_lshlrev_b32_e32 v40, 16, v36
	global_store_dwordx4 v151, v[36:39], s[56:57]
	v_add_f32_e32 v45, v152, v40
	v_fmac_f32_e32 v90, v40, v40
	v_and_b32_e32 v36, 0xffff0000, v36
	v_lshlrev_b32_e32 v41, 16, v37
	v_add_f32_e32 v40, v45, v36
	v_fmac_f32_e32 v90, v36, v36
	v_and_b32_e32 v37, 0xffff0000, v37
	v_add_f32_e32 v36, v40, v41
	v_fmac_f32_e32 v90, v41, v41
	v_lshlrev_b32_e32 v42, 16, v38
	v_add_f32_e32 v36, v36, v37
	v_fmac_f32_e32 v90, v37, v37
	v_and_b32_e32 v38, 0xffff0000, v38
	v_add_f32_e32 v36, v36, v42
	v_fmac_f32_e32 v90, v42, v42
	v_lshlrev_b32_e32 v43, 16, v39
	v_add_f32_e32 v36, v36, v38
	v_fmac_f32_e32 v90, v38, v38
	v_and_b32_e32 v39, 0xffff0000, v39
	v_add_f32_e32 v36, v36, v43
	v_fmac_f32_e32 v90, v43, v43
	v_add_f32_e32 v36, v36, v39
	v_fmac_f32_e32 v90, v39, v39
	v_pk_mul_f32 v[38:39], v[94:95], s[96:97] op_sel_hi:[1,0]
	v_lshlrev_b32_e32 v42, 16, v96
	v_fma_f32 v37, -v38, v38, v39
	v_max_f32_e32 v37, 0, v37
	v_add_f32_e32 v37, 0x3727c5ac, v37
	v_rsq_f32_e32 v40, v37
	v_and_b32_e32 v43, 0xffff0000, v96
	v_pk_mul_f32 v[46:47], v[20:21], v[40:41] op_sel_hi:[1,0]
	s_nop 0
	v_pk_fma_f32 v[50:51], v[38:39], v[46:47], v[24:25] op_sel_hi:[0,1,1] neg_lo:[1,0,0] neg_hi:[1,0,0]
	v_pk_fma_f32 v[42:43], v[42:43], v[46:47], v[50:51]
	v_pk_mul_f32 v[46:47], v[22:23], v[40:41] op_sel_hi:[1,0]
	v_pk_fma_f32 v[32:33], v[42:43], s[12:13], v[32:33] op_sel_hi:[1,0,1]
	v_lshlrev_b32_e32 v42, 16, v97
	v_and_b32_e32 v43, 0xffff0000, v97
	v_pk_fma_f32 v[50:51], v[38:39], v[46:47], v[26:27] op_sel_hi:[0,1,1] neg_lo:[1,0,0] neg_hi:[1,0,0]
	v_pk_fma_f32 v[42:43], v[42:43], v[46:47], v[50:51]
	v_pk_mul_f32 v[46:47], v[8:9], v[40:41] op_sel_hi:[1,0]
	v_pk_fma_f32 v[34:35], v[42:43], s[12:13], v[34:35] op_sel_hi:[1,0,1]
	v_lshlrev_b32_e32 v42, 16, v98
	v_and_b32_e32 v43, 0xffff0000, v98
	v_pk_fma_f32 v[50:51], v[38:39], v[46:47], v[12:13] op_sel_hi:[0,1,1] neg_lo:[1,0,0] neg_hi:[1,0,0]
	v_pk_fma_f32 v[42:43], v[42:43], v[46:47], v[50:51]
	v_pk_mul_f32 v[40:41], v[10:11], v[40:41] op_sel_hi:[1,0]
	v_pk_fma_f32 v[42:43], v[42:43], s[12:13], v[28:29] op_sel_hi:[1,0,1]
	v_lshlrev_b32_e32 v28, 16, v99
	v_and_b32_e32 v29, 0xffff0000, v99
	v_pk_fma_f32 v[38:39], v[38:39], v[40:41], v[14:15] op_sel_hi:[0,1,1] neg_lo:[1,0,0] neg_hi:[1,0,0]
	v_pk_fma_f32 v[28:29], v[28:29], v[40:41], v[38:39]
	s_nop 0
	v_pk_fma_f32 v[38:39], v[28:29], s[12:13], v[30:31] op_sel_hi:[1,0,1]
	v_cvt_pk_bf16_f32 v28, v32, v33
	v_cvt_pk_bf16_f32 v29, v34, v35
	v_cvt_pk_bf16_f32 v30, v42, v43
	v_cvt_pk_bf16_f32 v31, v38, v39
	v_lshlrev_b32_e32 v32, 16, v28
	global_store_dwordx4 v154, v[28:31], s[56:57]
	v_add_f32_e32 v37, v153, v32
	v_lshlrev_b32_e32 v33, 16, v29
	v_and_b32_e32 v28, 0xffff0000, v28
	v_fmac_f32_e32 v86, v32, v32
	v_add_f32_e32 v32, v37, v28
	v_and_b32_e32 v29, 0xffff0000, v29
	v_fmac_f32_e32 v86, v28, v28
	v_add_f32_e32 v28, v32, v33
	v_lshlrev_b32_e32 v34, 16, v30
	v_add_f32_e32 v28, v28, v29
	v_and_b32_e32 v30, 0xffff0000, v30
	v_fmac_f32_e32 v86, v33, v33
	v_add_f32_e32 v28, v28, v34
	v_lshlrev_b32_e32 v35, 16, v31
	v_fmac_f32_e32 v86, v29, v29
	v_add_f32_e32 v28, v28, v30
	v_and_b32_e32 v31, 0xffff0000, v31
	v_fmac_f32_e32 v86, v34, v34
	v_add_f32_e32 v28, v28, v35
	v_fmac_f32_e32 v86, v30, v30
	v_add_f32_e32 v30, v28, v31
	ds_read_b64 v[28:29], v177 offset:1408
	v_fmac_f32_e32 v86, v35, v35
	v_fmac_f32_e32 v86, v31, v31
	v_lshlrev_b32_e32 v34, 16, v16
	v_and_b32_e32 v35, 0xffff0000, v16
	s_waitcnt lgkmcnt(0)
	v_pk_mul_f32 v[28:29], v[28:29], s[96:97] op_sel_hi:[1,0]
	v_lshlrev_b32_e32 v16, 16, v17
	v_fma_f32 v31, -v28, v28, v29
	v_max_f32_e32 v31, 0, v31
	v_add_f32_e32 v31, 0x3727c5ac, v31
	v_rsq_f32_e32 v32, v31
	v_and_b32_e32 v17, 0xffff0000, v17
	v_pk_mul_f32 v[20:21], v[20:21], v[32:33] op_sel_hi:[1,0]
	s_nop 0
	v_pk_fma_f32 v[24:25], v[28:29], v[20:21], v[24:25] op_sel_hi:[0,1,1] neg_lo:[1,0,0] neg_hi:[1,0,0]
	v_pk_fma_f32 v[20:21], v[34:35], v[20:21], v[24:25]
	v_pk_mul_f32 v[8:9], v[8:9], v[32:33] op_sel_hi:[1,0]
	v_pk_fma_f32 v[4:5], v[20:21], s[12:13], v[4:5] op_sel_hi:[1,0,1]
	v_pk_mul_f32 v[20:21], v[22:23], v[32:33] op_sel_hi:[1,0]
	v_pk_fma_f32 v[12:13], v[28:29], v[8:9], v[12:13] op_sel_hi:[0,1,1] neg_lo:[1,0,0] neg_hi:[1,0,0]
	v_pk_fma_f32 v[22:23], v[28:29], v[20:21], v[26:27] op_sel_hi:[0,1,1] neg_lo:[1,0,0] neg_hi:[1,0,0]
	v_pk_fma_f32 v[16:17], v[16:17], v[20:21], v[22:23]
	v_pk_mul_f32 v[10:11], v[10:11], v[32:33] op_sel_hi:[1,0]
	v_pk_fma_f32 v[6:7], v[16:17], s[12:13], v[6:7] op_sel_hi:[1,0,1]
	v_lshlrev_b32_e32 v16, 16, v18
	v_and_b32_e32 v17, 0xffff0000, v18
	v_pk_fma_f32 v[8:9], v[16:17], v[8:9], v[12:13]
	v_pk_fma_f32 v[12:13], v[28:29], v[10:11], v[14:15] op_sel_hi:[0,1,1] neg_lo:[1,0,0] neg_hi:[1,0,0]
	v_pk_fma_f32 v[8:9], v[8:9], s[12:13], v[0:1] op_sel_hi:[1,0,1]
	v_lshlrev_b32_e32 v0, 16, v19
	v_and_b32_e32 v1, 0xffff0000, v19
	v_pk_fma_f32 v[0:1], v[0:1], v[10:11], v[12:13]
	s_nop 0
	v_pk_fma_f32 v[10:11], v[0:1], s[12:13], v[2:3] op_sel_hi:[1,0,1]
	v_cvt_pk_bf16_f32 v0, v4, v5
	v_cvt_pk_bf16_f32 v1, v6, v7
	v_cvt_pk_bf16_f32 v2, v8, v9
	v_cvt_pk_bf16_f32 v3, v10, v11
	v_lshlrev_b32_e32 v4, 16, v0
	global_store_dwordx4 v115, v[0:3], s[56:57]
	v_add_f32_e32 v8, v91, v4
	v_lshlrev_b32_e32 v5, 16, v1
	v_and_b32_e32 v0, 0xffff0000, v0
	v_fmac_f32_e32 v87, v4, v4
	v_add_f32_e32 v4, v8, v0
	v_and_b32_e32 v1, 0xffff0000, v1
	v_fmac_f32_e32 v87, v0, v0
	v_add_f32_e32 v0, v4, v5
	v_lshlrev_b32_e32 v6, 16, v2
	v_add_f32_e32 v0, v0, v1
	v_and_b32_e32 v2, 0xffff0000, v2
	v_add_f32_e32 v0, v0, v6
	v_lshlrev_b32_e32 v7, 16, v3
	v_add_f32_e32 v0, v0, v2
	v_and_b32_e32 v3, 0xffff0000, v3
	v_add_f32_e32 v0, v0, v7
	v_add_f32_e32 v28, v0, v3
	v_mbcnt_lo_u32_b32 v0, -1, 0
	v_mbcnt_hi_u32_b32 v0, -1, v0
	v_fmac_f32_e32 v87, v5, v5
	v_lshlrev_b32_e32 v0, 2, v0
	v_xor_b32_e32 v31, 64, v0
	v_fmac_f32_e32 v87, v1, v1
	ds_bpermute_b32 v24, v31, v30
	v_fmac_f32_e32 v87, v6, v6
	v_fmac_f32_e32 v87, v2, v2
	v_fmac_f32_e32 v87, v7, v7
	v_fmac_f32_e32 v87, v3, v3
	v_xor_b32_e32 v32, 0x80, v0
	ds_bpermute_b32 v0, v31, v76
	ds_bpermute_b32 v2, v31, v124
	ds_bpermute_b32 v4, v31, v68
	ds_bpermute_b32 v6, v31, v116
	ds_bpermute_b32 v8, v31, v60
	ds_bpermute_b32 v10, v31, v110
	ds_bpermute_b32 v12, v31, v48
	ds_bpermute_b32 v14, v31, v111
	ds_bpermute_b32 v16, v31, v44
	ds_bpermute_b32 v18, v31, v114
	ds_bpermute_b32 v20, v31, v36
	ds_bpermute_b32 v22, v31, v90
	s_waitcnt lgkmcnt(12)
	v_add_f32_e32 v24, v30, v24
	ds_bpermute_b32 v26, v31, v86
	ds_bpermute_b32 v29, v31, v28
	ds_bpermute_b32 v30, v31, v87
	s_waitcnt lgkmcnt(14)
	v_add_f32_e32 v0, v76, v0
	s_waitcnt lgkmcnt(13)
	v_add_f32_e32 v2, v124, v2
	s_waitcnt lgkmcnt(12)
	v_add_f32_e32 v4, v68, v4
	s_waitcnt lgkmcnt(11)
	v_add_f32_e32 v6, v116, v6
	s_waitcnt lgkmcnt(10)
	v_add_f32_e32 v8, v60, v8
	s_waitcnt lgkmcnt(9)
	v_add_f32_e32 v10, v110, v10
	s_waitcnt lgkmcnt(8)
	v_add_f32_e32 v12, v48, v12
	s_waitcnt lgkmcnt(7)
	v_add_f32_e32 v14, v111, v14
	s_waitcnt lgkmcnt(6)
	v_add_f32_e32 v16, v44, v16
	s_waitcnt lgkmcnt(5)
	v_add_f32_e32 v18, v114, v18
	s_waitcnt lgkmcnt(4)
	v_add_f32_e32 v20, v36, v20
	s_waitcnt lgkmcnt(3)
	v_add_f32_e32 v22, v90, v22
	s_waitcnt lgkmcnt(2)
	v_add_f32_e32 v26, v86, v26
	s_waitcnt lgkmcnt(1)
	v_add_f32_e32 v28, v28, v29
	s_waitcnt lgkmcnt(0)
	v_add_f32_e32 v30, v87, v30
	ds_bpermute_b32 v1, v32, v0
	ds_bpermute_b32 v3, v32, v2
	ds_bpermute_b32 v5, v32, v4
	ds_bpermute_b32 v7, v32, v6
	ds_bpermute_b32 v9, v32, v8
	ds_bpermute_b32 v11, v32, v10
	ds_bpermute_b32 v13, v32, v12
	ds_bpermute_b32 v15, v32, v14
	ds_bpermute_b32 v17, v32, v16
	ds_bpermute_b32 v19, v32, v18
	ds_bpermute_b32 v21, v32, v20
	ds_bpermute_b32 v23, v32, v22
	ds_bpermute_b32 v25, v32, v24
	ds_bpermute_b32 v27, v32, v26
	ds_bpermute_b32 v29, v32, v28
	ds_bpermute_b32 v31, v32, v30
	s_and_saveexec_b64 s[4:5], vcc
	s_movk_i32 s81, 0x5000
	s_cbranch_execz .LBB0_1575
	s_waitcnt lgkmcnt(14)
	v_add_f32_e32 v0, v0, v1
	v_lshlrev_b32_e32 v1, 3, v176
	s_waitcnt lgkmcnt(8)
	v_add_f32_e32 v14, v14, v15
	v_add_f32_e32 v12, v12, v13
	v_add_f32_e32 v10, v10, v11
	v_add_f32_e32 v8, v8, v9
	v_add_f32_e32 v6, v6, v7
	v_add_f32_e32 v4, v4, v5
	v_add_f32_e32 v2, v2, v3
	global_atomic_add_f32 v1, v0, s[58:59]
	global_atomic_add_f32 v1, v2, s[58:59] offset:4
	global_atomic_add_f32 v1, v4, s[58:59] offset:128
	global_atomic_add_f32 v1, v6, s[58:59] offset:132
	global_atomic_add_f32 v1, v8, s[58:59] offset:256
	global_atomic_add_f32 v1, v10, s[58:59] offset:260
	global_atomic_add_f32 v1, v12, s[58:59] offset:384
	global_atomic_add_f32 v1, v14, s[58:59] offset:388
	s_waitcnt lgkmcnt(7)
	v_add_f32_e32 v16, v16, v17
	v_add_u32_e32 v0, 0x400, v1
	s_waitcnt lgkmcnt(5)
	v_add_f32_e32 v20, v20, v21
	v_add_f32_e32 v18, v18, v19
	global_atomic_add_f32 v0, v16, s[58:59]
	global_atomic_add_f32 v0, v18, s[58:59] offset:4
	v_add_u32_e32 v0, 0x480, v1
	s_waitcnt lgkmcnt(3)
	v_add_f32_e32 v24, v24, v25
	v_add_f32_e32 v22, v22, v23
	global_atomic_add_f32 v0, v20, s[58:59]
	global_atomic_add_f32 v0, v22, s[58:59] offset:4
	v_add_u32_e32 v0, 0x500, v1
	s_waitcnt lgkmcnt(1)
	v_add_f32_e32 v28, v28, v29
	v_add_f32_e32 v26, v26, v27
	global_atomic_add_f32 v0, v24, s[58:59]
	global_atomic_add_f32 v0, v26, s[58:59] offset:4
	v_add_u32_e32 v0, 0x580, v1
	s_waitcnt lgkmcnt(0)
	v_add_f32_e32 v30, v30, v31
	global_atomic_add_f32 v0, v28, s[58:59]
	global_atomic_add_f32 v0, v30, s[58:59] offset:4
